# in-proj rotary epilogues: second-half table loads issued mid first half into dead registers, counted vmcnt
# speedup vs baseline: 1.0103x; 1.0006x over previous
.LBB0_151:
	s_andn2_b64 vcc, exec, s[0:1]
	s_cbranch_vccnz .LBB0_153
	s_lshr_b32 s0, s75, 3
	s_mulk_i32 s0, 0x880
	s_lshl_b32 s1, s75, 8
	s_and_b32 s1, s1, 0x700
	s_add_i32 s0, s0, s66
	s_add_i32 s0, s0, s1
	v_or_b32_e32 v152, s0, v176
	s_lshl_b32 s0, s69, 8
	v_lshl_or_b32 v0, v175, 3, s0
	v_or_b32_e32 v154, s61, v0
	s_nop 0
	v_and_b32_e32 v0, 0x7e, v154
	v_lshlrev_b32_e32 v0, 2, v0
	v_lshl_add_u64 v[170:171], s[42:43], 0, v[0:1]
	v_mul_hi_i32 v0, v152, s63
	v_lshrrev_b32_e32 v130, 31, v0
	v_ashrrev_i32_e32 v0, 10, v0
	v_add_u32_e32 v0, v0, v130
	v_mul_i32_i24_e32 v0, 0x880, v0
	v_sub_u32_e32 v166, v152, v0
	v_ashrrev_i32_e32 v167, 31, v166
	v_lshlrev_b64 v[130:131], 9, v[166:167]
	v_add_u32_e32 v153, 16, v152
	v_lshl_add_u64 v[130:131], v[170:171], 0, v[130:131]
	v_mul_hi_i32 v0, v153, s63
	global_load_dwordx4 v[178:181], v[130:131], off offset:16
	global_load_dwordx4 v[182:185], v[130:131], off
	v_lshrrev_b32_e32 v130, 31, v0
	v_ashrrev_i32_e32 v0, 10, v0
	v_add_u32_e32 v0, v0, v130
	v_mul_i32_i24_e32 v0, 0x880, v0
	v_sub_u32_e32 v198, v153, v0
	v_ashrrev_i32_e32 v199, 31, v198
	v_lshlrev_b64 v[130:131], 9, v[198:199]
	v_add_u32_e32 v177, 32, v152
	v_lshl_add_u64 v[130:131], v[170:171], 0, v[130:131]
	v_mul_hi_i32 v0, v177, s63
	global_load_dwordx4 v[186:189], v[130:131], off offset:16
	global_load_dwordx4 v[190:193], v[130:131], off
	v_lshrrev_b32_e32 v130, 31, v0
	v_ashrrev_i32_e32 v0, 10, v0
	v_add_u32_e32 v0, v0, v130
	v_mul_i32_i24_e32 v0, 0x880, v0
	v_sub_u32_e32 v200, v177, v0
	v_ashrrev_i32_e32 v201, 31, v200
	v_lshlrev_b64 v[130:131], 9, v[200:201]
	v_add_u32_e32 v201, 48, v152
	v_lshl_add_u64 v[130:131], v[170:171], 0, v[130:131]
	v_mul_hi_i32 v0, v201, s63
	global_load_dwordx4 v[138:141], v[130:131], off offset:16
	global_load_dwordx4 v[142:145], v[130:131], off
	v_lshrrev_b32_e32 v130, 31, v0
	v_ashrrev_i32_e32 v0, 10, v0
	v_add_u32_e32 v0, v0, v130
	v_mul_i32_i24_e32 v0, 0x880, v0
	v_sub_u32_e32 v172, v201, v0
	v_ashrrev_i32_e32 v173, 31, v172
	v_lshlrev_b64 v[130:131], 9, v[172:173]
	v_lshl_add_u64 v[134:135], v[170:171], 0, v[130:131]
	global_load_dwordx4 v[130:133], v[134:135], off offset:16
	s_nop 0
	global_load_dwordx4 v[134:137], v[134:135], off
	s_waitcnt vmcnt(0)
	v_pk_mul_f32 v[204:205], v[122:123], v[178:179] op_sel:[0,1]
	v_cmp_lt_i32_e32 vcc, s11, v166
	v_pk_fma_f32 v[206:207], v[122:123], v[178:179], v[204:205] op_sel:[0,0,1] op_sel_hi:[1,0,0] neg_lo:[0,0,1] neg_hi:[0,0,1]
	v_pk_fma_f32 v[204:205], v[122:123], v[178:179], v[204:205] op_sel:[0,0,1] op_sel_hi:[1,0,0]
	v_pk_mul_f32 v[166:167], v[126:127], v[182:183] op_sel:[0,1]
	v_mov_b32_e32 v204, v181
	v_pk_mul_f32 v[208:209], v[124:125], v[204:205] op_sel_hi:[1,0]
	v_pk_fma_f32 v[168:169], v[126:127], v[182:183], v[166:167] op_sel:[0,0,1] op_sel_hi:[1,0,0] neg_lo:[0,0,1] neg_hi:[0,0,1]
	v_pk_fma_f32 v[166:167], v[126:127], v[182:183], v[166:167] op_sel:[0,0,1] op_sel_hi:[1,0,0]
	v_mov_b32_e32 v202, v185
	v_pk_fma_f32 v[212:213], v[124:125], v[180:181], v[208:209] op_sel:[0,0,1] op_sel_hi:[1,0,0] neg_lo:[0,0,1] neg_hi:[0,0,1]
	v_pk_fma_f32 v[208:209], v[124:125], v[180:181], v[208:209] op_sel:[0,0,1] op_sel_hi:[1,0,0]
	v_cndmask_b32_e32 v0, 0, v231, vcc
	v_pk_mul_f32 v[194:195], v[128:129], v[202:203] op_sel_hi:[1,0]
	v_mov_b32_e32 v169, v167
	v_mov_b32_e32 v213, v209
	s_movk_i32 s0, 0x1bff
	v_pk_fma_f32 v[196:197], v[128:129], v[184:185], v[194:195] op_sel:[0,0,1] op_sel_hi:[1,0,0] neg_lo:[0,0,1] neg_hi:[0,0,1]
	v_pk_fma_f32 v[194:195], v[128:129], v[184:185], v[194:195] op_sel:[0,0,1] op_sel_hi:[1,0,0]
	v_pk_mul_f32 v[216:217], v[0:1], v[168:169] op_sel_hi:[0,1]
	v_mov_b32_e32 v207, v205
	v_pk_mul_f32 v[222:223], v[0:1], v[212:213] op_sel_hi:[0,1]
	v_cmp_lt_i32_e64 s[0:1], s0, v154
	v_mov_b32_e32 v197, v195
	v_pk_mul_f32 v[220:221], v[0:1], v[206:207] op_sel_hi:[0,1]
	v_cndmask_b32_e64 v155, v209, v223, s[0:1]
	v_cndmask_b32_e64 v166, v212, v222, s[0:1]
	v_cndmask_b32_e64 v167, v167, v217, s[0:1]
	v_cndmask_b32_e64 v168, v168, v216, s[0:1]
	v_pk_mul_f32 v[218:219], v[0:1], v[196:197] op_sel_hi:[0,1]
	v_cndmask_b32_e64 v169, v205, v221, s[0:1]
	v_cndmask_b32_e64 v173, v206, v220, s[0:1]
	v_cvt_pk_bf16_f32 v194, v168, v167
	v_cvt_pk_bf16_f32 v197, v166, v155
	v_mov_b64_e32 v[166:167], s[8:9]
	v_ashrrev_i32_e32 v155, 31, v154
	v_cndmask_b32_e64 v181, v195, v219, s[0:1]
	v_cndmask_b32_e64 v185, v196, v218, s[0:1]
	v_cvt_pk_bf16_f32 v196, v173, v169
	v_mad_i64_i32 v[206:207], s[6:7], v152, s47, v[166:167]
	v_lshlrev_b64 v[168:169], 1, v[154:155]
	v_cvt_pk_bf16_f32 v195, v185, v181
	v_lshl_add_u64 v[206:207], v[206:207], 0, v[168:169]
	global_store_dwordx4 v[206:207], v[194:197], off
	s_nop 1
	v_pk_mul_f32 v[194:195], v[118:119], v[182:183] op_sel:[0,1]
	s_movk_i32 s6, 0x1b7f
	v_pk_fma_f32 v[196:197], v[118:119], v[182:183], v[194:195] op_sel:[0,0,1] op_sel_hi:[1,0,0] neg_lo:[0,0,1] neg_hi:[0,0,1]
	v_pk_fma_f32 v[182:183], v[118:119], v[182:183], v[194:195] op_sel:[0,0,1] op_sel_hi:[1,0,0]
	v_pk_mul_f32 v[194:195], v[120:121], v[202:203] op_sel_hi:[1,0]
	v_mov_b32_e32 v197, v183
	v_pk_fma_f32 v[202:203], v[120:121], v[184:185], v[194:195] op_sel:[0,0,1] op_sel_hi:[1,0,0] neg_lo:[0,0,1] neg_hi:[0,0,1]
	v_pk_fma_f32 v[184:185], v[120:121], v[184:185], v[194:195] op_sel:[0,0,1] op_sel_hi:[1,0,0]
	v_pk_mul_f32 v[194:195], v[110:111], v[178:179] op_sel:[0,1]
	v_mov_b32_e32 v203, v185
	v_pk_fma_f32 v[208:209], v[110:111], v[178:179], v[194:195] op_sel:[0,0,1] op_sel_hi:[1,0,0] neg_lo:[0,0,1] neg_hi:[0,0,1]
	v_pk_fma_f32 v[178:179], v[110:111], v[178:179], v[194:195] op_sel:[0,0,1] op_sel_hi:[1,0,0]
	v_pk_mul_f32 v[194:195], v[112:113], v[204:205] op_sel_hi:[1,0]
	v_mov_b32_e32 v209, v179
	v_pk_fma_f32 v[204:205], v[112:113], v[180:181], v[194:195] op_sel:[0,0,1] op_sel_hi:[1,0,0] neg_lo:[0,0,1] neg_hi:[0,0,1]
	v_pk_fma_f32 v[180:181], v[112:113], v[180:181], v[194:195] op_sel:[0,0,1] op_sel_hi:[1,0,0]
	v_cmp_lt_i32_e32 vcc, s6, v154
	v_mov_b32_e32 v205, v181
	v_pk_mul_f32 v[154:155], v[0:1], v[196:197] op_sel_hi:[0,1]
	v_pk_mul_f32 v[194:195], v[0:1], v[202:203] op_sel_hi:[0,1]
	v_pk_mul_f32 v[212:213], v[0:1], v[208:209] op_sel_hi:[0,1]
	v_pk_mul_f32 v[216:217], v[0:1], v[204:205] op_sel_hi:[0,1]
	v_cndmask_b32_e32 v0, v181, v217, vcc
	v_cndmask_b32_e32 v173, v204, v216, vcc
	v_cndmask_b32_e32 v180, v179, v213, vcc
	v_cndmask_b32_e32 v181, v208, v212, vcc
	v_cndmask_b32_e32 v179, v185, v195, vcc
	v_cndmask_b32_e32 v182, v202, v194, vcc
	v_cndmask_b32_e32 v155, v183, v155, vcc
	v_cndmask_b32_e32 v154, v196, v154, vcc
	v_cvt_pk_bf16_f32 v178, v154, v155
	v_cvt_pk_bf16_f32 v179, v182, v179
	v_cvt_pk_bf16_f32 v180, v181, v180
	v_cvt_pk_bf16_f32 v181, v173, v0
	global_store_dwordx4 v[206:207], v[178:181], off offset:256
	v_pk_mul_f32 v[154:155], v[114:115], v[190:191] op_sel:[0,1]
	v_pk_mul_f32 v[184:185], v[106:107], v[186:187] op_sel:[0,1]
	v_pk_fma_f32 v[178:179], v[114:115], v[190:191], v[154:155] op_sel:[0,0,1] op_sel_hi:[1,0,0] neg_lo:[0,0,1] neg_hi:[0,0,1]
	v_pk_fma_f32 v[154:155], v[114:115], v[190:191], v[154:155] op_sel:[0,0,1] op_sel_hi:[1,0,0]
	v_pk_fma_f32 v[194:195], v[106:107], v[186:187], v[184:185] op_sel:[0,0,1] op_sel_hi:[1,0,0] neg_lo:[0,0,1] neg_hi:[0,0,1]
	v_pk_fma_f32 v[184:185], v[106:107], v[186:187], v[184:185] op_sel:[0,0,1] op_sel_hi:[1,0,0]
	v_mov_b32_e32 v154, v193
	v_mov_b32_e32 v184, v189
	v_pk_mul_f32 v[180:181], v[116:117], v[154:155] op_sel_hi:[1,0]
	v_pk_mul_f32 v[196:197], v[108:109], v[184:185] op_sel_hi:[1,0]
	v_cmp_lt_i32_e64 s[38:39], s11, v198
	v_pk_fma_f32 v[182:183], v[116:117], v[192:193], v[180:181] op_sel:[0,0,1] op_sel_hi:[1,0,0] neg_lo:[0,0,1] neg_hi:[0,0,1]
	v_pk_fma_f32 v[180:181], v[116:117], v[192:193], v[180:181] op_sel:[0,0,1] op_sel_hi:[1,0,0]
	v_pk_fma_f32 v[198:199], v[108:109], v[188:189], v[196:197] op_sel:[0,0,1] op_sel_hi:[1,0,0] neg_lo:[0,0,1] neg_hi:[0,0,1]
	v_pk_fma_f32 v[196:197], v[108:109], v[188:189], v[196:197] op_sel:[0,0,1] op_sel_hi:[1,0,0]
	v_cndmask_b32_e64 v0, 0, v231, s[38:39]
	v_mov_b32_e32 v183, v181
	v_mov_b32_e32 v199, v197
	v_mov_b32_e32 v179, v155
	v_pk_mul_f32 v[204:205], v[0:1], v[182:183] op_sel_hi:[0,1]
	v_mov_b32_e32 v195, v185
	v_pk_mul_f32 v[208:209], v[0:1], v[198:199] op_sel_hi:[0,1]
	v_pk_mul_f32 v[202:203], v[0:1], v[178:179] op_sel_hi:[0,1]
	v_pk_mul_f32 v[206:207], v[0:1], v[194:195] op_sel_hi:[0,1]
	v_cndmask_b32_e64 v173, v197, v209, s[0:1]
	v_cndmask_b32_e64 v183, v198, v208, s[0:1]
	v_cndmask_b32_e64 v179, v181, v205, s[0:1]
	v_cndmask_b32_e64 v181, v182, v204, s[0:1]
	v_cndmask_b32_e64 v180, v185, v207, s[0:1]
	v_cndmask_b32_e64 v185, v194, v206, s[0:1]
	v_cndmask_b32_e64 v155, v155, v203, s[0:1]
	v_cndmask_b32_e64 v178, v178, v202, s[0:1]
	v_cvt_pk_bf16_f32 v179, v181, v179
	v_cvt_pk_bf16_f32 v181, v183, v173
	v_mad_i64_i32 v[182:183], s[6:7], v153, s47, v[166:167]
	v_cvt_pk_bf16_f32 v178, v178, v155
	v_cvt_pk_bf16_f32 v180, v185, v180
	v_lshl_add_u64 v[182:183], v[182:183], 0, v[168:169]
	global_store_dwordx4 v[182:183], v[178:181], off
	s_nop 1
	v_pk_mul_f32 v[178:179], v[102:103], v[190:191] op_sel:[0,1]
	v_pk_mul_f32 v[154:155], v[104:105], v[154:155] op_sel_hi:[1,0]
	v_pk_fma_f32 v[180:181], v[102:103], v[190:191], v[178:179] op_sel:[0,0,1] op_sel_hi:[1,0,0] neg_lo:[0,0,1] neg_hi:[0,0,1]
	v_pk_fma_f32 v[178:179], v[102:103], v[190:191], v[178:179] op_sel:[0,0,1] op_sel_hi:[1,0,0]
	v_pk_fma_f32 v[190:191], v[104:105], v[192:193], v[154:155] op_sel:[0,0,1] op_sel_hi:[1,0,0] neg_lo:[0,0,1] neg_hi:[0,0,1]
	v_pk_fma_f32 v[154:155], v[104:105], v[192:193], v[154:155] op_sel:[0,0,1] op_sel_hi:[1,0,0]
	v_pk_mul_f32 v[192:193], v[94:95], v[186:187] op_sel:[0,1]
	v_pk_mul_f32 v[184:185], v[96:97], v[184:185] op_sel_hi:[1,0]
	v_pk_fma_f32 v[194:195], v[94:95], v[186:187], v[192:193] op_sel:[0,0,1] op_sel_hi:[1,0,0] neg_lo:[0,0,1] neg_hi:[0,0,1]
	v_pk_fma_f32 v[186:187], v[94:95], v[186:187], v[192:193] op_sel:[0,0,1] op_sel_hi:[1,0,0]
	v_pk_fma_f32 v[192:193], v[96:97], v[188:189], v[184:185] op_sel:[0,0,1] op_sel_hi:[1,0,0] neg_lo:[0,0,1] neg_hi:[0,0,1]
	v_pk_fma_f32 v[184:185], v[96:97], v[188:189], v[184:185] op_sel:[0,0,1] op_sel_hi:[1,0,0]
	v_mov_b32_e32 v181, v179
	v_mov_b32_e32 v191, v155
	v_mov_b32_e32 v195, v187
	v_mov_b32_e32 v193, v185
	v_pk_mul_f32 v[188:189], v[0:1], v[180:181] op_sel_hi:[0,1]
	v_pk_mul_f32 v[196:197], v[0:1], v[190:191] op_sel_hi:[0,1]
	v_pk_mul_f32 v[198:199], v[0:1], v[194:195] op_sel_hi:[0,1]
	v_pk_mul_f32 v[202:203], v[0:1], v[192:193] op_sel_hi:[0,1]
	v_cndmask_b32_e32 v0, v185, v203, vcc
	v_cndmask_b32_e32 v153, v192, v202, vcc
	v_cndmask_b32_e32 v154, v187, v199, vcc
	v_cndmask_b32_e32 v173, v194, v198, vcc
	v_cndmask_b32_e32 v155, v155, v197, vcc
	v_cndmask_b32_e32 v181, v190, v196, vcc
	v_cndmask_b32_e32 v178, v179, v189, vcc
	v_cndmask_b32_e32 v179, v180, v188, vcc
	v_cvt_pk_bf16_f32 v178, v179, v178
	v_cvt_pk_bf16_f32 v179, v181, v155
	v_cvt_pk_bf16_f32 v180, v173, v154
	v_cvt_pk_bf16_f32 v181, v153, v0
	global_store_dwordx4 v[182:183], v[178:181], off offset:256
	s_nop 1
	v_add_u32_e32 v147, 0x80, v152
	v_mul_hi_i32 v0, v147, s63
	v_lshrrev_b32_e32 v94, 31, v0
	v_ashrrev_i32_e32 v0, 10, v0
	v_add_u32_e32 v0, v0, v94
	v_mul_i32_i24_e32 v0, 0x880, v0
	v_sub_u32_e32 v224, v147, v0
	v_ashrrev_i32_e32 v225, 31, v224
	v_lshlrev_b64 v[94:95], 9, v[224:225]
	v_add_u32_e32 v176, 0x90, v152
	v_lshl_add_u64 v[94:95], v[170:171], 0, v[94:95]
	v_mul_hi_i32 v0, v176, s63
	global_load_dwordx4 v[114:117], v[94:95], off offset:16
	global_load_dwordx4 v[118:121], v[94:95], off
	v_lshrrev_b32_e32 v94, 31, v0
	v_ashrrev_i32_e32 v0, 10, v0
	v_add_u32_e32 v0, v0, v94
	v_mul_i32_i24_e32 v0, 0x880, v0
	v_sub_u32_e32 v228, v176, v0
	v_ashrrev_i32_e32 v229, 31, v228
	v_lshlrev_b64 v[94:95], 9, v[228:229]
	v_add_u32_e32 v233, 0xa0, v152
	v_lshl_add_u64 v[94:95], v[170:171], 0, v[94:95]
	v_mul_hi_i32 v0, v233, s63
	global_load_dwordx4 v[122:125], v[94:95], off offset:16
	global_load_dwordx4 v[126:129], v[94:95], off
	v_lshrrev_b32_e32 v94, 31, v0
	v_ashrrev_i32_e32 v0, 10, v0
	v_add_u32_e32 v0, v0, v94
	v_mul_i32_i24_e32 v0, 0x880, v0
	v_sub_u32_e32 v238, v233, v0
	v_ashrrev_i32_e32 v239, 31, v238
	v_lshlrev_b64 v[94:95], 9, v[238:239]
	v_add_u32_e32 v252, 0xb0, v152
	v_lshl_add_u64 v[94:95], v[170:171], 0, v[94:95]
	v_mul_hi_i32 v0, v252, s63
	global_load_dwordx4 v[106:109], v[94:95], off offset:16
	global_load_dwordx4 v[110:113], v[94:95], off
	v_lshrrev_b32_e32 v94, 31, v0
	v_ashrrev_i32_e32 v0, 10, v0
	v_add_u32_e32 v0, v0, v94
	v_mul_i32_i24_e32 v0, 0x880, v0
	v_sub_u32_e32 v226, v252, v0
	v_ashrrev_i32_e32 v227, 31, v226
	v_lshlrev_b64 v[94:95], 9, v[226:227]
	v_lshl_add_u64 v[102:103], v[170:171], 0, v[94:95]
	global_load_dwordx4 v[94:97], v[102:103], off offset:16
	s_nop 0
	global_load_dwordx4 v[102:105], v[102:103], off
	v_pk_mul_f32 v[154:155], v[98:99], v[142:143] op_sel:[0,1]
	v_pk_mul_f32 v[184:185], v[90:91], v[138:139] op_sel:[0,1]
	v_pk_fma_f32 v[178:179], v[98:99], v[142:143], v[154:155] op_sel:[0,0,1] op_sel_hi:[1,0,0] neg_lo:[0,0,1] neg_hi:[0,0,1]
	v_pk_fma_f32 v[154:155], v[98:99], v[142:143], v[154:155] op_sel:[0,0,1] op_sel_hi:[1,0,0]
	v_pk_fma_f32 v[186:187], v[90:91], v[138:139], v[184:185] op_sel:[0,0,1] op_sel_hi:[1,0,0] neg_lo:[0,0,1] neg_hi:[0,0,1]
	v_pk_fma_f32 v[184:185], v[90:91], v[138:139], v[184:185] op_sel:[0,0,1] op_sel_hi:[1,0,0]
	v_mov_b32_e32 v154, v145
	v_mov_b32_e32 v184, v141
	v_pk_mul_f32 v[180:181], v[100:101], v[154:155] op_sel_hi:[1,0]
	v_pk_mul_f32 v[188:189], v[92:93], v[184:185] op_sel_hi:[1,0]
	v_cmp_lt_i32_e64 s[38:39], s11, v200
	v_pk_fma_f32 v[182:183], v[100:101], v[144:145], v[180:181] op_sel:[0,0,1] op_sel_hi:[1,0,0] neg_lo:[0,0,1] neg_hi:[0,0,1]
	v_pk_fma_f32 v[180:181], v[100:101], v[144:145], v[180:181] op_sel:[0,0,1] op_sel_hi:[1,0,0]
	v_pk_fma_f32 v[190:191], v[92:93], v[140:141], v[188:189] op_sel:[0,0,1] op_sel_hi:[1,0,0] neg_lo:[0,0,1] neg_hi:[0,0,1]
	v_pk_fma_f32 v[188:189], v[92:93], v[140:141], v[188:189] op_sel:[0,0,1] op_sel_hi:[1,0,0]
	v_cndmask_b32_e64 v0, 0, v231, s[38:39]
	v_mov_b32_e32 v179, v155
	v_mov_b32_e32 v183, v181
	v_mov_b32_e32 v187, v185
	v_mov_b32_e32 v191, v189
	v_pk_mul_f32 v[192:193], v[0:1], v[178:179] op_sel_hi:[0,1]
	v_pk_mul_f32 v[194:195], v[0:1], v[182:183] op_sel_hi:[0,1]
	v_pk_mul_f32 v[196:197], v[0:1], v[186:187] op_sel_hi:[0,1]
	v_pk_mul_f32 v[198:199], v[0:1], v[190:191] op_sel_hi:[0,1]
	v_cndmask_b32_e64 v141, v189, v199, s[0:1]
	v_cndmask_b32_e64 v145, v190, v198, s[0:1]
	v_cndmask_b32_e64 v153, v185, v197, s[0:1]
	v_cndmask_b32_e64 v173, v186, v196, s[0:1]
	v_cndmask_b32_e64 v179, v181, v195, s[0:1]
	v_cndmask_b32_e64 v180, v182, v194, s[0:1]
	v_cndmask_b32_e64 v155, v155, v193, s[0:1]
	v_cndmask_b32_e64 v178, v178, v192, s[0:1]
	v_mad_i64_i32 v[182:183], s[6:7], v177, s47, v[166:167]
	v_cvt_pk_bf16_f32 v178, v178, v155
	v_cvt_pk_bf16_f32 v179, v180, v179
	v_cvt_pk_bf16_f32 v180, v173, v153
	v_cvt_pk_bf16_f32 v181, v145, v141
	v_lshl_add_u64 v[182:183], v[182:183], 0, v[168:169]
	global_store_dwordx4 v[182:183], v[178:181], off
	s_nop 1
	v_pk_mul_f32 v[178:179], v[86:87], v[142:143] op_sel:[0,1]
	v_pk_mul_f32 v[154:155], v[88:89], v[154:155] op_sel_hi:[1,0]
	v_pk_fma_f32 v[180:181], v[86:87], v[142:143], v[178:179] op_sel:[0,0,1] op_sel_hi:[1,0,0] neg_lo:[0,0,1] neg_hi:[0,0,1]
	v_pk_fma_f32 v[142:143], v[86:87], v[142:143], v[178:179] op_sel:[0,0,1] op_sel_hi:[1,0,0]
	v_pk_fma_f32 v[178:179], v[88:89], v[144:145], v[154:155] op_sel:[0,0,1] op_sel_hi:[1,0,0] neg_lo:[0,0,1] neg_hi:[0,0,1]
	v_pk_fma_f32 v[144:145], v[88:89], v[144:145], v[154:155] op_sel:[0,0,1] op_sel_hi:[1,0,0]
	v_pk_mul_f32 v[154:155], v[78:79], v[138:139] op_sel:[0,1]
	v_mov_b32_e32 v181, v143
	v_pk_fma_f32 v[186:187], v[78:79], v[138:139], v[154:155] op_sel:[0,0,1] op_sel_hi:[1,0,0] neg_lo:[0,0,1] neg_hi:[0,0,1]
	v_pk_fma_f32 v[138:139], v[78:79], v[138:139], v[154:155] op_sel:[0,0,1] op_sel_hi:[1,0,0]
	v_pk_mul_f32 v[154:155], v[80:81], v[184:185] op_sel_hi:[1,0]
	v_mov_b32_e32 v179, v145
	v_pk_fma_f32 v[184:185], v[80:81], v[140:141], v[154:155] op_sel:[0,0,1] op_sel_hi:[1,0,0] neg_lo:[0,0,1] neg_hi:[0,0,1]
	v_pk_fma_f32 v[140:141], v[80:81], v[140:141], v[154:155] op_sel:[0,0,1] op_sel_hi:[1,0,0]
	v_mov_b32_e32 v187, v139
	v_mov_b32_e32 v185, v141
	v_pk_mul_f32 v[154:155], v[0:1], v[180:181] op_sel_hi:[0,1]
	v_pk_mul_f32 v[188:189], v[0:1], v[178:179] op_sel_hi:[0,1]
	v_pk_mul_f32 v[190:191], v[0:1], v[186:187] op_sel_hi:[0,1]
	v_pk_mul_f32 v[192:193], v[0:1], v[184:185] op_sel_hi:[0,1]
	v_cndmask_b32_e32 v0, v141, v193, vcc
	v_cndmask_b32_e32 v141, v184, v192, vcc
	v_cndmask_b32_e32 v140, v139, v191, vcc
	v_cndmask_b32_e32 v142, v186, v190, vcc
	v_cndmask_b32_e32 v139, v145, v189, vcc
	v_cndmask_b32_e32 v144, v178, v188, vcc
	v_cndmask_b32_e32 v138, v143, v155, vcc
	v_cndmask_b32_e32 v143, v180, v154, vcc
	v_cvt_pk_bf16_f32 v138, v143, v138
	v_cvt_pk_bf16_f32 v139, v144, v139
	v_cvt_pk_bf16_f32 v140, v142, v140
	v_cvt_pk_bf16_f32 v141, v141, v0
	global_store_dwordx4 v[182:183], v[138:141], off offset:256
	v_mov_b32_e32 v142, v137
	v_pk_mul_f32 v[144:145], v[84:85], v[142:143] op_sel_hi:[1,0]
	v_cmp_lt_i32_e64 s[38:39], s11, v172
	v_pk_fma_f32 v[154:155], v[84:85], v[136:137], v[144:145] op_sel:[0,0,1] op_sel_hi:[1,0,0] neg_lo:[0,0,1] neg_hi:[0,0,1]
	v_pk_fma_f32 v[144:145], v[84:85], v[136:137], v[144:145] op_sel:[0,0,1] op_sel_hi:[1,0,0]
	v_pk_mul_f32 v[138:139], v[82:83], v[134:135] op_sel:[0,1]
	v_mov_b32_e32 v144, v133
	v_pk_mul_f32 v[172:173], v[74:75], v[130:131] op_sel:[0,1]
	v_pk_mul_f32 v[180:181], v[76:77], v[144:145] op_sel_hi:[1,0]
	v_pk_fma_f32 v[140:141], v[82:83], v[134:135], v[138:139] op_sel:[0,0,1] op_sel_hi:[1,0,0] neg_lo:[0,0,1] neg_hi:[0,0,1]
	v_pk_fma_f32 v[138:139], v[82:83], v[134:135], v[138:139] op_sel:[0,0,1] op_sel_hi:[1,0,0]
	v_pk_fma_f32 v[178:179], v[74:75], v[130:131], v[172:173] op_sel:[0,0,1] op_sel_hi:[1,0,0] neg_lo:[0,0,1] neg_hi:[0,0,1]
	v_pk_fma_f32 v[172:173], v[74:75], v[130:131], v[172:173] op_sel:[0,0,1] op_sel_hi:[1,0,0]
	v_pk_fma_f32 v[182:183], v[76:77], v[132:133], v[180:181] op_sel:[0,0,1] op_sel_hi:[1,0,0] neg_lo:[0,0,1] neg_hi:[0,0,1]
	v_pk_fma_f32 v[180:181], v[76:77], v[132:133], v[180:181] op_sel:[0,0,1] op_sel_hi:[1,0,0]
	v_cndmask_b32_e64 v0, 0, v231, s[38:39]
	v_mov_b32_e32 v141, v139
	v_mov_b32_e32 v155, v145
	v_mov_b32_e32 v179, v173
	v_mov_b32_e32 v183, v181
	v_pk_mul_f32 v[184:185], v[0:1], v[140:141] op_sel_hi:[0,1]
	v_pk_mul_f32 v[186:187], v[0:1], v[154:155] op_sel_hi:[0,1]
	v_pk_mul_f32 v[188:189], v[0:1], v[178:179] op_sel_hi:[0,1]
	v_pk_mul_f32 v[190:191], v[0:1], v[182:183] op_sel_hi:[0,1]
	v_cndmask_b32_e64 v133, v181, v191, s[0:1]
	v_cndmask_b32_e64 v137, v182, v190, s[0:1]
	v_cndmask_b32_e64 v141, v173, v189, s[0:1]
	v_cndmask_b32_e64 v143, v178, v188, s[0:1]
	v_cndmask_b32_e64 v145, v145, v187, s[0:1]
	v_cndmask_b32_e64 v153, v154, v186, s[0:1]
	v_cndmask_b32_e64 v138, v139, v185, s[0:1]
	v_cndmask_b32_e64 v139, v140, v184, s[0:1]
	v_mad_i64_i32 v[154:155], s[6:7], v201, s47, v[166:167]
	v_cvt_pk_bf16_f32 v138, v139, v138
	v_cvt_pk_bf16_f32 v139, v153, v145
	v_cvt_pk_bf16_f32 v140, v143, v141
	v_cvt_pk_bf16_f32 v141, v137, v133
	v_lshl_add_u64 v[154:155], v[154:155], 0, v[168:169]
	global_store_dwordx4 v[154:155], v[138:141], off
	s_nop 1
	v_pk_mul_f32 v[138:139], v[70:71], v[134:135] op_sel:[0,1]
	s_nop 0
	v_pk_fma_f32 v[140:141], v[70:71], v[134:135], v[138:139] op_sel:[0,0,1] op_sel_hi:[1,0,0] neg_lo:[0,0,1] neg_hi:[0,0,1]
	v_pk_fma_f32 v[134:135], v[70:71], v[134:135], v[138:139] op_sel:[0,0,1] op_sel_hi:[1,0,0]
	v_pk_mul_f32 v[138:139], v[72:73], v[142:143] op_sel_hi:[1,0]
	v_mov_b32_e32 v141, v135
	v_pk_fma_f32 v[142:143], v[72:73], v[136:137], v[138:139] op_sel:[0,0,1] op_sel_hi:[1,0,0] neg_lo:[0,0,1] neg_hi:[0,0,1]
	v_pk_fma_f32 v[136:137], v[72:73], v[136:137], v[138:139] op_sel:[0,0,1] op_sel_hi:[1,0,0]
	v_pk_mul_f32 v[138:139], v[66:67], v[130:131] op_sel:[0,1]
	v_mov_b32_e32 v143, v137
	v_pk_fma_f32 v[172:173], v[66:67], v[130:131], v[138:139] op_sel:[0,0,1] op_sel_hi:[1,0,0] neg_lo:[0,0,1] neg_hi:[0,0,1]
	v_pk_fma_f32 v[130:131], v[66:67], v[130:131], v[138:139] op_sel:[0,0,1] op_sel_hi:[1,0,0]
	v_pk_mul_f32 v[138:139], v[68:69], v[144:145] op_sel_hi:[1,0]
	v_mov_b32_e32 v173, v131
	v_pk_fma_f32 v[144:145], v[68:69], v[132:133], v[138:139] op_sel:[0,0,1] op_sel_hi:[1,0,0] neg_lo:[0,0,1] neg_hi:[0,0,1]
	v_pk_fma_f32 v[132:133], v[68:69], v[132:133], v[138:139] op_sel:[0,0,1] op_sel_hi:[1,0,0]
	v_pk_mul_f32 v[138:139], v[0:1], v[140:141] op_sel_hi:[0,1]
	v_mov_b32_e32 v145, v133
	v_pk_mul_f32 v[178:179], v[0:1], v[142:143] op_sel_hi:[0,1]
	v_pk_mul_f32 v[180:181], v[0:1], v[172:173] op_sel_hi:[0,1]
	v_pk_mul_f32 v[182:183], v[0:1], v[144:145] op_sel_hi:[0,1]
	v_cndmask_b32_e32 v0, v133, v183, vcc
	v_cndmask_b32_e32 v133, v144, v182, vcc
	v_cndmask_b32_e32 v132, v131, v181, vcc
	v_cndmask_b32_e32 v134, v172, v180, vcc
	v_cndmask_b32_e32 v131, v137, v179, vcc
	v_cndmask_b32_e32 v136, v142, v178, vcc
	v_cndmask_b32_e32 v130, v135, v139, vcc
	v_cndmask_b32_e32 v135, v140, v138, vcc
	v_cvt_pk_bf16_f32 v130, v135, v130
	v_cvt_pk_bf16_f32 v131, v136, v131
	v_cvt_pk_bf16_f32 v132, v134, v132
	v_cvt_pk_bf16_f32 v133, v133, v0
	global_store_dwordx4 v[154:155], v[130:133], off offset:256
	s_waitcnt vmcnt(4)
	v_mov_b32_e32 v170, v121
	v_pk_mul_f32 v[198:199], v[64:65], v[170:171] op_sel_hi:[1,0]
	v_pk_mul_f32 v[152:153], v[62:63], v[118:119] op_sel:[0,1]
	v_pk_fma_f32 v[200:201], v[64:65], v[120:121], v[198:199] op_sel:[0,0,1] op_sel_hi:[1,0,0] neg_lo:[0,0,1] neg_hi:[0,0,1]
	v_pk_fma_f32 v[198:199], v[64:65], v[120:121], v[198:199] op_sel:[0,0,1] op_sel_hi:[1,0,0]
	v_pk_mul_f32 v[202:203], v[58:59], v[114:115] op_sel:[0,1]
	v_mov_b32_e32 v198, v117
	v_pk_mul_f32 v[206:207], v[60:61], v[198:199] op_sel_hi:[1,0]
	v_cmp_lt_i32_e64 s[38:39], s11, v224
	v_pk_fma_f32 v[154:155], v[62:63], v[118:119], v[152:153] op_sel:[0,0,1] op_sel_hi:[1,0,0] neg_lo:[0,0,1] neg_hi:[0,0,1]
	v_pk_fma_f32 v[152:153], v[62:63], v[118:119], v[152:153] op_sel:[0,0,1] op_sel_hi:[1,0,0]
	v_pk_fma_f32 v[204:205], v[58:59], v[114:115], v[202:203] op_sel:[0,0,1] op_sel_hi:[1,0,0] neg_lo:[0,0,1] neg_hi:[0,0,1]
	v_pk_fma_f32 v[202:203], v[58:59], v[114:115], v[202:203] op_sel:[0,0,1] op_sel_hi:[1,0,0]
	v_pk_fma_f32 v[208:209], v[60:61], v[116:117], v[206:207] op_sel:[0,0,1] op_sel_hi:[1,0,0] neg_lo:[0,0,1] neg_hi:[0,0,1]
	v_pk_fma_f32 v[206:207], v[60:61], v[116:117], v[206:207] op_sel:[0,0,1] op_sel_hi:[1,0,0]
	v_cndmask_b32_e64 v0, 0, v231, s[38:39]
	v_mov_b32_e32 v155, v153
	v_mov_b32_e32 v201, v199
	v_mov_b32_e32 v205, v203
	v_mov_b32_e32 v209, v207
	v_pk_mul_f32 v[212:213], v[0:1], v[154:155] op_sel_hi:[0,1]
	v_pk_mul_f32 v[216:217], v[0:1], v[200:201] op_sel_hi:[0,1]
	v_pk_mul_f32 v[218:219], v[0:1], v[204:205] op_sel_hi:[0,1]
	v_pk_mul_f32 v[220:221], v[0:1], v[208:209] op_sel_hi:[0,1]
	v_cndmask_b32_e64 v155, v207, v221, s[0:1]
	v_cndmask_b32_e64 v171, v208, v220, s[0:1]
	v_cndmask_b32_e64 v173, v203, v219, s[0:1]
	v_cndmask_b32_e64 v181, v204, v218, s[0:1]
	v_cndmask_b32_e64 v185, v199, v217, s[0:1]
	v_cndmask_b32_e64 v195, v200, v216, s[0:1]
	v_cndmask_b32_e64 v152, v153, v213, s[0:1]
	v_cndmask_b32_e64 v153, v154, v212, s[0:1]
	v_mad_i64_i32 v[200:201], s[6:7], v147, s47, v[166:167]
	v_cvt_pk_bf16_f32 v152, v153, v152
	v_cvt_pk_bf16_f32 v153, v195, v185
	v_cvt_pk_bf16_f32 v154, v181, v173
	v_cvt_pk_bf16_f32 v155, v171, v155
	v_lshl_add_u64 v[200:201], v[200:201], 0, v[168:169]
	global_store_dwordx4 v[200:201], v[152:155], off
	s_nop 1
	v_pk_mul_f32 v[152:153], v[54:55], v[118:119] op_sel:[0,1]
	v_pk_mul_f32 v[170:171], v[56:57], v[170:171] op_sel_hi:[1,0]
	v_pk_fma_f32 v[154:155], v[54:55], v[118:119], v[152:153] op_sel:[0,0,1] op_sel_hi:[1,0,0] neg_lo:[0,0,1] neg_hi:[0,0,1]
	v_pk_fma_f32 v[152:153], v[54:55], v[118:119], v[152:153] op_sel:[0,0,1] op_sel_hi:[1,0,0]
	v_pk_fma_f32 v[182:183], v[56:57], v[120:121], v[170:171] op_sel:[0,0,1] op_sel_hi:[1,0,0] neg_lo:[0,0,1] neg_hi:[0,0,1]
	v_pk_fma_f32 v[170:171], v[56:57], v[120:121], v[170:171] op_sel:[0,0,1] op_sel_hi:[1,0,0]
	v_pk_mul_f32 v[184:185], v[46:47], v[114:115] op_sel:[0,1]
	v_mov_b32_e32 v155, v153
	v_pk_fma_f32 v[202:203], v[46:47], v[114:115], v[184:185] op_sel:[0,0,1] op_sel_hi:[1,0,0] neg_lo:[0,0,1] neg_hi:[0,0,1]
	v_pk_fma_f32 v[178:179], v[46:47], v[114:115], v[184:185] op_sel:[0,0,1] op_sel_hi:[1,0,0]
	v_pk_mul_f32 v[184:185], v[48:49], v[198:199] op_sel_hi:[1,0]
	v_mov_b32_e32 v183, v171
	v_pk_fma_f32 v[198:199], v[48:49], v[116:117], v[184:185] op_sel:[0,0,1] op_sel_hi:[1,0,0] neg_lo:[0,0,1] neg_hi:[0,0,1]
	v_pk_fma_f32 v[180:181], v[48:49], v[116:117], v[184:185] op_sel:[0,0,1] op_sel_hi:[1,0,0]
	v_mov_b32_e32 v203, v179
	v_mov_b32_e32 v199, v181
	v_pk_mul_f32 v[184:185], v[0:1], v[154:155] op_sel_hi:[0,1]
	v_pk_mul_f32 v[204:205], v[0:1], v[182:183] op_sel_hi:[0,1]
	v_pk_mul_f32 v[206:207], v[0:1], v[202:203] op_sel_hi:[0,1]
	v_pk_mul_f32 v[208:209], v[0:1], v[198:199] op_sel_hi:[0,1]
	v_cndmask_b32_e32 v0, v181, v209, vcc
	v_cndmask_b32_e32 v155, v198, v208, vcc
	v_cndmask_b32_e32 v170, v179, v207, vcc
	v_cndmask_b32_e32 v173, v202, v206, vcc
	v_cndmask_b32_e32 v171, v171, v205, vcc
	v_cndmask_b32_e32 v177, v182, v204, vcc
	v_cndmask_b32_e32 v152, v153, v185, vcc
	v_cndmask_b32_e32 v153, v154, v184, vcc
	v_cvt_pk_bf16_f32 v152, v153, v152
	v_cvt_pk_bf16_f32 v153, v177, v171
	v_cvt_pk_bf16_f32 v154, v173, v170
	v_cvt_pk_bf16_f32 v155, v155, v0
	global_store_dwordx4 v[200:201], v[152:155], off offset:256
	v_mov_b32_e32 v170, v129
	v_pk_mul_f32 v[178:179], v[52:53], v[170:171] op_sel_hi:[1,0]
	v_pk_mul_f32 v[152:153], v[50:51], v[126:127] op_sel:[0,1]
	v_pk_fma_f32 v[180:181], v[52:53], v[128:129], v[178:179] op_sel:[0,0,1] op_sel_hi:[1,0,0] neg_lo:[0,0,1] neg_hi:[0,0,1]
	v_pk_fma_f32 v[178:179], v[52:53], v[128:129], v[178:179] op_sel:[0,0,1] op_sel_hi:[1,0,0]
	v_cmp_lt_i32_e64 s[38:39], s11, v228
	v_mov_b32_e32 v178, v125
	v_pk_fma_f32 v[154:155], v[50:51], v[126:127], v[152:153] op_sel:[0,0,1] op_sel_hi:[1,0,0] neg_lo:[0,0,1] neg_hi:[0,0,1]
	v_pk_fma_f32 v[152:153], v[50:51], v[126:127], v[152:153] op_sel:[0,0,1] op_sel_hi:[1,0,0]
	v_pk_mul_f32 v[182:183], v[42:43], v[122:123] op_sel:[0,1]
	v_pk_mul_f32 v[194:195], v[44:45], v[178:179] op_sel_hi:[1,0]
	v_cndmask_b32_e64 v0, 0, v231, s[38:39]
	v_pk_fma_f32 v[184:185], v[42:43], v[122:123], v[182:183] op_sel:[0,0,1] op_sel_hi:[1,0,0] neg_lo:[0,0,1] neg_hi:[0,0,1]
	v_pk_fma_f32 v[182:183], v[42:43], v[122:123], v[182:183] op_sel:[0,0,1] op_sel_hi:[1,0,0]
	v_pk_fma_f32 v[198:199], v[44:45], v[124:125], v[194:195] op_sel:[0,0,1] op_sel_hi:[1,0,0] neg_lo:[0,0,1] neg_hi:[0,0,1]
	v_pk_fma_f32 v[194:195], v[44:45], v[124:125], v[194:195] op_sel:[0,0,1] op_sel_hi:[1,0,0]
	v_mov_b32_e32 v155, v153
	v_mov_b32_e32 v181, v179
	v_pk_mul_f32 v[200:201], v[0:1], v[154:155] op_sel_hi:[0,1]
	v_pk_mul_f32 v[202:203], v[0:1], v[180:181] op_sel_hi:[0,1]
	v_mov_b32_e32 v185, v183
	v_mov_b32_e32 v199, v195
	v_pk_mul_f32 v[204:205], v[0:1], v[184:185] op_sel_hi:[0,1]
	v_pk_mul_f32 v[206:207], v[0:1], v[198:199] op_sel_hi:[0,1]
	v_cndmask_b32_e64 v179, v179, v203, s[0:1]
	v_cndmask_b32_e64 v180, v180, v202, s[0:1]
	v_cndmask_b32_e64 v152, v153, v201, s[0:1]
	v_cndmask_b32_e64 v153, v154, v200, s[0:1]
	v_cndmask_b32_e64 v155, v195, v207, s[0:1]
	v_cndmask_b32_e64 v171, v198, v206, s[0:1]
	v_cndmask_b32_e64 v173, v183, v205, s[0:1]
	v_cndmask_b32_e64 v177, v184, v204, s[0:1]
	v_cvt_pk_bf16_f32 v152, v153, v152
	v_cvt_pk_bf16_f32 v153, v180, v179
	v_mad_i64_i32 v[180:181], s[6:7], v176, s47, v[166:167]
	v_cvt_pk_bf16_f32 v154, v177, v173
	v_cvt_pk_bf16_f32 v155, v171, v155
	v_lshl_add_u64 v[180:181], v[180:181], 0, v[168:169]
	global_store_dwordx4 v[180:181], v[152:155], off
	s_nop 1
	v_pk_mul_f32 v[152:153], v[38:39], v[126:127] op_sel:[0,1]
	v_pk_mul_f32 v[170:171], v[40:41], v[170:171] op_sel_hi:[1,0]
	v_pk_mul_f32 v[184:185], v[30:31], v[122:123] op_sel:[0,1]
	v_pk_mul_f32 v[178:179], v[32:33], v[178:179] op_sel_hi:[1,0]
	v_pk_fma_f32 v[154:155], v[38:39], v[126:127], v[152:153] op_sel:[0,0,1] op_sel_hi:[1,0,0] neg_lo:[0,0,1] neg_hi:[0,0,1]
	v_pk_fma_f32 v[152:153], v[38:39], v[126:127], v[152:153] op_sel:[0,0,1] op_sel_hi:[1,0,0]
	v_pk_fma_f32 v[182:183], v[40:41], v[128:129], v[170:171] op_sel:[0,0,1] op_sel_hi:[1,0,0] neg_lo:[0,0,1] neg_hi:[0,0,1]
	v_pk_fma_f32 v[170:171], v[40:41], v[128:129], v[170:171] op_sel:[0,0,1] op_sel_hi:[1,0,0]
	v_pk_fma_f32 v[190:191], v[30:31], v[122:123], v[184:185] op_sel:[0,0,1] op_sel_hi:[1,0,0] neg_lo:[0,0,1] neg_hi:[0,0,1]
	v_pk_fma_f32 v[184:185], v[30:31], v[122:123], v[184:185] op_sel:[0,0,1] op_sel_hi:[1,0,0]
	v_pk_fma_f32 v[186:187], v[32:33], v[124:125], v[178:179] op_sel:[0,0,1] op_sel_hi:[1,0,0] neg_lo:[0,0,1] neg_hi:[0,0,1]
	v_pk_fma_f32 v[178:179], v[32:33], v[124:125], v[178:179] op_sel:[0,0,1] op_sel_hi:[1,0,0]
	v_mov_b32_e32 v155, v153
	v_mov_b32_e32 v183, v171
	v_mov_b32_e32 v191, v185
	v_mov_b32_e32 v187, v179
	v_pk_mul_f32 v[188:189], v[0:1], v[154:155] op_sel_hi:[0,1]
	v_pk_mul_f32 v[192:193], v[0:1], v[182:183] op_sel_hi:[0,1]
	v_pk_mul_f32 v[194:195], v[0:1], v[190:191] op_sel_hi:[0,1]
	v_pk_mul_f32 v[198:199], v[0:1], v[186:187] op_sel_hi:[0,1]
	v_cndmask_b32_e32 v0, v179, v199, vcc
	v_cndmask_b32_e32 v155, v186, v198, vcc
	v_cndmask_b32_e32 v170, v185, v195, vcc
	v_cndmask_b32_e32 v173, v190, v194, vcc
	v_cndmask_b32_e32 v171, v171, v193, vcc
	v_cndmask_b32_e32 v177, v182, v192, vcc
	v_cndmask_b32_e32 v152, v153, v189, vcc
	v_cndmask_b32_e32 v153, v154, v188, vcc
	v_cvt_pk_bf16_f32 v152, v153, v152
	v_cvt_pk_bf16_f32 v153, v177, v171
	v_cvt_pk_bf16_f32 v154, v173, v170
	v_cvt_pk_bf16_f32 v155, v155, v0
	global_store_dwordx4 v[180:181], v[152:155], off offset:256
	v_mov_b32_e32 v170, v113
	v_pk_mul_f32 v[178:179], v[36:37], v[170:171] op_sel_hi:[1,0]
	v_pk_mul_f32 v[152:153], v[34:35], v[110:111] op_sel:[0,1]
	v_pk_fma_f32 v[180:181], v[36:37], v[112:113], v[178:179] op_sel:[0,0,1] op_sel_hi:[1,0,0] neg_lo:[0,0,1] neg_hi:[0,0,1]
	v_pk_fma_f32 v[178:179], v[36:37], v[112:113], v[178:179] op_sel:[0,0,1] op_sel_hi:[1,0,0]
	v_pk_mul_f32 v[182:183], v[26:27], v[106:107] op_sel:[0,1]
	v_mov_b32_e32 v178, v109
	v_pk_mul_f32 v[186:187], v[28:29], v[178:179] op_sel_hi:[1,0]
	v_cmp_lt_i32_e64 s[38:39], s11, v238
	v_pk_fma_f32 v[154:155], v[34:35], v[110:111], v[152:153] op_sel:[0,0,1] op_sel_hi:[1,0,0] neg_lo:[0,0,1] neg_hi:[0,0,1]
	v_pk_fma_f32 v[152:153], v[34:35], v[110:111], v[152:153] op_sel:[0,0,1] op_sel_hi:[1,0,0]
	v_pk_fma_f32 v[184:185], v[26:27], v[106:107], v[182:183] op_sel:[0,0,1] op_sel_hi:[1,0,0] neg_lo:[0,0,1] neg_hi:[0,0,1]
	v_pk_fma_f32 v[182:183], v[26:27], v[106:107], v[182:183] op_sel:[0,0,1] op_sel_hi:[1,0,0]
	v_pk_fma_f32 v[188:189], v[28:29], v[108:109], v[186:187] op_sel:[0,0,1] op_sel_hi:[1,0,0] neg_lo:[0,0,1] neg_hi:[0,0,1]
	v_pk_fma_f32 v[186:187], v[28:29], v[108:109], v[186:187] op_sel:[0,0,1] op_sel_hi:[1,0,0]
	v_cndmask_b32_e64 v0, 0, v231, s[38:39]
	v_mov_b32_e32 v155, v153
	v_mov_b32_e32 v181, v179
	v_mov_b32_e32 v185, v183
	v_mov_b32_e32 v189, v187
	v_pk_mul_f32 v[190:191], v[0:1], v[154:155] op_sel_hi:[0,1]
	v_pk_mul_f32 v[192:193], v[0:1], v[180:181] op_sel_hi:[0,1]
	v_pk_mul_f32 v[194:195], v[0:1], v[184:185] op_sel_hi:[0,1]
	v_pk_mul_f32 v[196:197], v[0:1], v[188:189] op_sel_hi:[0,1]
	v_cndmask_b32_e64 v141, v187, v197, s[0:1]
	v_cndmask_b32_e64 v145, v188, v196, s[0:1]
	v_cndmask_b32_e64 v155, v183, v195, s[0:1]
	v_cndmask_b32_e64 v171, v184, v194, s[0:1]
	v_cndmask_b32_e64 v173, v179, v193, s[0:1]
	v_cndmask_b32_e64 v177, v180, v192, s[0:1]
	v_cndmask_b32_e64 v152, v153, v191, s[0:1]
	v_cndmask_b32_e64 v153, v154, v190, s[0:1]
	v_mad_i64_i32 v[180:181], s[6:7], v233, s47, v[166:167]
	v_cvt_pk_bf16_f32 v152, v153, v152
	v_cvt_pk_bf16_f32 v153, v177, v173
	v_cvt_pk_bf16_f32 v154, v171, v155
	v_cvt_pk_bf16_f32 v155, v145, v141
	v_lshl_add_u64 v[180:181], v[180:181], 0, v[168:169]
	global_store_dwordx4 v[180:181], v[152:155], off
	s_nop 1
	v_pk_mul_f32 v[152:153], v[22:23], v[110:111] op_sel:[0,1]
	s_nop 0
	v_pk_fma_f32 v[154:155], v[22:23], v[110:111], v[152:153] op_sel:[0,0,1] op_sel_hi:[1,0,0] neg_lo:[0,0,1] neg_hi:[0,0,1]
	v_pk_fma_f32 v[142:143], v[22:23], v[110:111], v[152:153] op_sel:[0,0,1] op_sel_hi:[1,0,0]
	v_pk_mul_f32 v[152:153], v[24:25], v[170:171] op_sel_hi:[1,0]
	v_mov_b32_e32 v155, v143
	v_pk_fma_f32 v[170:171], v[24:25], v[112:113], v[152:153] op_sel:[0,0,1] op_sel_hi:[1,0,0] neg_lo:[0,0,1] neg_hi:[0,0,1]
	v_pk_fma_f32 v[144:145], v[24:25], v[112:113], v[152:153] op_sel:[0,0,1] op_sel_hi:[1,0,0]
	v_pk_mul_f32 v[152:153], v[14:15], v[106:107] op_sel:[0,1]
	v_mov_b32_e32 v171, v145
	v_pk_fma_f32 v[182:183], v[14:15], v[106:107], v[152:153] op_sel:[0,0,1] op_sel_hi:[1,0,0] neg_lo:[0,0,1] neg_hi:[0,0,1]
	v_pk_fma_f32 v[138:139], v[14:15], v[106:107], v[152:153] op_sel:[0,0,1] op_sel_hi:[1,0,0]
	v_pk_mul_f32 v[152:153], v[16:17], v[178:179] op_sel_hi:[1,0]
	v_mov_b32_e32 v183, v139
	v_pk_fma_f32 v[178:179], v[16:17], v[108:109], v[152:153] op_sel:[0,0,1] op_sel_hi:[1,0,0] neg_lo:[0,0,1] neg_hi:[0,0,1]
	v_pk_fma_f32 v[140:141], v[16:17], v[108:109], v[152:153] op_sel:[0,0,1] op_sel_hi:[1,0,0]
	v_pk_mul_f32 v[152:153], v[0:1], v[154:155] op_sel_hi:[0,1]
	v_mov_b32_e32 v179, v141
	v_pk_mul_f32 v[184:185], v[0:1], v[170:171] op_sel_hi:[0,1]
	v_pk_mul_f32 v[186:187], v[0:1], v[182:183] op_sel_hi:[0,1]
	v_pk_mul_f32 v[188:189], v[0:1], v[178:179] op_sel_hi:[0,1]
	v_cndmask_b32_e32 v0, v141, v189, vcc
	v_cndmask_b32_e32 v141, v178, v188, vcc
	v_cndmask_b32_e32 v140, v139, v187, vcc
	v_cndmask_b32_e32 v142, v182, v186, vcc
	v_cndmask_b32_e32 v139, v145, v185, vcc
	v_cndmask_b32_e32 v144, v170, v184, vcc
	v_cndmask_b32_e32 v138, v143, v153, vcc
	v_cndmask_b32_e32 v143, v154, v152, vcc
	v_cvt_pk_bf16_f32 v138, v143, v138
	v_cvt_pk_bf16_f32 v139, v144, v139
	v_cvt_pk_bf16_f32 v140, v142, v140
	v_cvt_pk_bf16_f32 v141, v141, v0
	global_store_dwordx4 v[180:181], v[138:141], off offset:256
	v_mov_b32_e32 v142, v105
	v_pk_mul_f32 v[144:145], v[20:21], v[142:143] op_sel_hi:[1,0]
	v_pk_mul_f32 v[138:139], v[18:19], v[102:103] op_sel:[0,1]
	v_pk_fma_f32 v[152:153], v[20:21], v[104:105], v[144:145] op_sel:[0,0,1] op_sel_hi:[1,0,0] neg_lo:[0,0,1] neg_hi:[0,0,1]
	v_pk_fma_f32 v[144:145], v[20:21], v[104:105], v[144:145] op_sel:[0,0,1] op_sel_hi:[1,0,0]
	v_cmp_lt_i32_e64 s[38:39], s11, v226
	v_mov_b32_e32 v144, v97
	v_pk_fma_f32 v[140:141], v[18:19], v[102:103], v[138:139] op_sel:[0,0,1] op_sel_hi:[1,0,0] neg_lo:[0,0,1] neg_hi:[0,0,1]
	v_pk_fma_f32 v[138:139], v[18:19], v[102:103], v[138:139] op_sel:[0,0,1] op_sel_hi:[1,0,0]
	v_pk_mul_f32 v[154:155], v[10:11], v[94:95] op_sel:[0,1]
	v_pk_mul_f32 v[172:173], v[12:13], v[144:145] op_sel_hi:[1,0]
	v_cndmask_b32_e64 v0, 0, v231, s[38:39]
	v_pk_fma_f32 v[170:171], v[10:11], v[94:95], v[154:155] op_sel:[0,0,1] op_sel_hi:[1,0,0] neg_lo:[0,0,1] neg_hi:[0,0,1]
	v_pk_fma_f32 v[154:155], v[10:11], v[94:95], v[154:155] op_sel:[0,0,1] op_sel_hi:[1,0,0]
	v_pk_fma_f32 v[178:179], v[12:13], v[96:97], v[172:173] op_sel:[0,0,1] op_sel_hi:[1,0,0] neg_lo:[0,0,1] neg_hi:[0,0,1]
	v_pk_fma_f32 v[172:173], v[12:13], v[96:97], v[172:173] op_sel:[0,0,1] op_sel_hi:[1,0,0]
	v_mov_b32_e32 v141, v139
	v_mov_b32_e32 v153, v145
	v_pk_mul_f32 v[180:181], v[0:1], v[140:141] op_sel_hi:[0,1]
	v_pk_mul_f32 v[182:183], v[0:1], v[152:153] op_sel_hi:[0,1]
	v_mov_b32_e32 v171, v155
	v_mov_b32_e32 v179, v173
	v_pk_mul_f32 v[184:185], v[0:1], v[170:171] op_sel_hi:[0,1]
	v_pk_mul_f32 v[186:187], v[0:1], v[178:179] op_sel_hi:[0,1]
	v_cndmask_b32_e64 v145, v145, v183, s[0:1]
	v_cndmask_b32_e64 v152, v152, v182, s[0:1]
	v_cndmask_b32_e64 v138, v139, v181, s[0:1]
	v_cndmask_b32_e64 v139, v140, v180, s[0:1]
	v_cndmask_b32_e64 v133, v173, v187, s[0:1]
	v_cndmask_b32_e64 v137, v178, v186, s[0:1]
	v_cndmask_b32_e64 v141, v155, v185, s[0:1]
	v_cndmask_b32_e64 v143, v170, v184, s[0:1]
	v_cvt_pk_bf16_f32 v138, v139, v138
	v_cvt_pk_bf16_f32 v139, v152, v145
	v_mad_i64_i32 v[152:153], s[0:1], v252, s47, v[166:167]
	v_cvt_pk_bf16_f32 v140, v143, v141
	v_cvt_pk_bf16_f32 v141, v137, v133
	v_lshl_add_u64 v[152:153], v[152:153], 0, v[168:169]
	global_store_dwordx4 v[152:153], v[138:141], off
	s_nop 1
	v_pk_mul_f32 v[138:139], v[6:7], v[102:103] op_sel:[0,1]
	s_nop 0
	v_pk_fma_f32 v[140:141], v[6:7], v[102:103], v[138:139] op_sel:[0,0,1] op_sel_hi:[1,0,0] neg_lo:[0,0,1] neg_hi:[0,0,1]
	v_pk_fma_f32 v[134:135], v[6:7], v[102:103], v[138:139] op_sel:[0,0,1] op_sel_hi:[1,0,0]
	v_pk_mul_f32 v[138:139], v[8:9], v[142:143] op_sel_hi:[1,0]
	v_mov_b32_e32 v141, v135
	v_pk_fma_f32 v[142:143], v[8:9], v[104:105], v[138:139] op_sel:[0,0,1] op_sel_hi:[1,0,0] neg_lo:[0,0,1] neg_hi:[0,0,1]
	v_pk_fma_f32 v[136:137], v[8:9], v[104:105], v[138:139] op_sel:[0,0,1] op_sel_hi:[1,0,0]
	v_pk_mul_f32 v[138:139], v[2:3], v[94:95] op_sel:[0,1]
	v_mov_b32_e32 v143, v137
	v_pk_fma_f32 v[154:155], v[2:3], v[94:95], v[138:139] op_sel:[0,0,1] op_sel_hi:[1,0,0] neg_lo:[0,0,1] neg_hi:[0,0,1]
	v_pk_fma_f32 v[130:131], v[2:3], v[94:95], v[138:139] op_sel:[0,0,1] op_sel_hi:[1,0,0]
	v_pk_mul_f32 v[138:139], v[4:5], v[144:145] op_sel_hi:[1,0]
	v_mov_b32_e32 v155, v131
	v_pk_fma_f32 v[144:145], v[4:5], v[96:97], v[138:139] op_sel:[0,0,1] op_sel_hi:[1,0,0] neg_lo:[0,0,1] neg_hi:[0,0,1]
	v_pk_fma_f32 v[132:133], v[4:5], v[96:97], v[138:139] op_sel:[0,0,1] op_sel_hi:[1,0,0]
	v_pk_mul_f32 v[138:139], v[0:1], v[140:141] op_sel_hi:[0,1]
	v_mov_b32_e32 v145, v133
	v_pk_mul_f32 v[166:167], v[0:1], v[142:143] op_sel_hi:[0,1]
	v_pk_mul_f32 v[168:169], v[0:1], v[154:155] op_sel_hi:[0,1]
	v_pk_mul_f32 v[170:171], v[0:1], v[144:145] op_sel_hi:[0,1]
	v_cndmask_b32_e32 v0, v133, v171, vcc
	v_cndmask_b32_e32 v133, v144, v170, vcc
	v_cndmask_b32_e32 v132, v131, v169, vcc
	v_cndmask_b32_e32 v134, v154, v168, vcc
	v_cndmask_b32_e32 v131, v137, v167, vcc
	v_cndmask_b32_e32 v136, v142, v166, vcc
	v_cndmask_b32_e32 v130, v135, v139, vcc
	v_cndmask_b32_e32 v135, v140, v138, vcc
	v_cvt_pk_bf16_f32 v130, v135, v130
	v_cvt_pk_bf16_f32 v131, v136, v131
	v_cvt_pk_bf16_f32 v132, v134, v132
	v_cvt_pk_bf16_f32 v133, v133, v0
	global_store_dwordx4 v[152:153], v[130:133], off offset:256

.LBB0_157:
	s_andn2_b64 vcc, exec, s[0:1]
	s_cbranch_vccnz .LBB0_128
	s_lshr_b32 s0, s75, 3
	s_mulk_i32 s0, 0x880
	s_lshl_b32 s1, s75, 8
	s_and_b32 s1, s1, 0x700
	s_add_i32 s0, s0, s66
	s_add_i32 s0, s0, s1
	v_or_b32_e32 v196, s0, v176
	s_lshl_b32 s0, s69, 8
	v_lshl_or_b32 v0, v175, 3, s0
	v_or_b32_e32 v144, s61, v0
	s_nop 0
	v_and_b32_e32 v0, 62, v144
	v_lshlrev_b32_e32 v0, 2, v0
	v_lshl_add_u64 v[130:131], s[28:29], 0, v[0:1]
	v_mul_hi_i32 v0, v196, s63
	v_lshrrev_b32_e32 v132, 31, v0
	v_ashrrev_i32_e32 v0, 10, v0
	v_add_u32_e32 v0, v0, v132
	v_mul_i32_i24_e32 v0, 0x880, v0
	v_add_u32_e32 v175, 16, v196
	v_sub_u32_e32 v132, v196, v0
	v_mul_hi_i32 v0, v175, s63
	v_lshrrev_b32_e32 v140, 31, v0
	v_ashrrev_i32_e32 v0, 10, v0
	v_add_u32_e32 v0, v0, v140
	v_mul_i32_i24_e32 v0, 0x880, v0
	v_add_u32_e32 v197, 32, v196
	v_sub_u32_e32 v140, v175, v0
	v_mul_hi_i32 v0, v197, s63
	v_lshrrev_b32_e32 v145, 31, v0
	v_ashrrev_i32_e32 v0, 10, v0
	v_add_u32_e32 v0, v0, v145
	v_mul_i32_i24_e32 v0, 0x880, v0
	v_add_u32_e32 v198, 48, v196
	v_sub_u32_e32 v166, v197, v0
	v_mul_hi_i32 v0, v198, s63
	v_lshrrev_b32_e32 v145, 31, v0
	v_ashrrev_i32_e32 v0, 10, v0
	v_add_u32_e32 v0, v0, v145
	v_mul_i32_i24_e32 v0, 0x880, v0
	v_sub_u32_e32 v176, v198, v0
	v_ashrrev_i32_e32 v133, 31, v132
	v_ashrrev_i32_e32 v141, 31, v140
	v_ashrrev_i32_e32 v167, 31, v166
	v_ashrrev_i32_e32 v177, 31, v176
	v_lshlrev_b64 v[132:133], 8, v[132:133]
	v_lshlrev_b64 v[140:141], 8, v[140:141]
	v_lshlrev_b64 v[166:167], 8, v[166:167]
	v_lshlrev_b64 v[176:177], 8, v[176:177]
	v_lshl_add_u64 v[136:137], v[130:131], 0, v[132:133]
	v_lshl_add_u64 v[152:153], v[130:131], 0, v[140:141]
	v_lshl_add_u64 v[170:171], v[130:131], 0, v[166:167]
	v_lshl_add_u64 v[180:181], v[130:131], 0, v[176:177]
	global_load_dwordx4 v[132:135], v[136:137], off offset:16
	s_nop 0
	global_load_dwordx4 v[136:139], v[136:137], off
	s_nop 0
	global_load_dwordx4 v[140:143], v[152:153], off offset:16
	s_nop 0
	global_load_dwordx4 v[152:155], v[152:153], off
	s_nop 0
	global_load_dwordx4 v[166:169], v[170:171], off offset:16
	s_nop 0
	global_load_dwordx4 v[170:173], v[170:171], off
	s_nop 0
	global_load_dwordx4 v[176:179], v[180:181], off offset:16
	s_nop 0
	global_load_dwordx4 v[180:183], v[180:181], off
	s_waitcnt vmcnt(0)
	v_pk_mul_f32 v[184:185], v[126:127], v[136:137] op_sel:[0,1]
	v_mov_b32_e32 v0, v139
	v_pk_fma_f32 v[186:187], v[126:127], v[136:137], v[184:185] op_sel:[0,0,1] op_sel_hi:[1,1,0] neg_lo:[0,0,1] neg_hi:[0,0,1]
	v_pk_fma_f32 v[126:127], v[126:127], v[136:137], v[184:185] op_sel:[0,0,1] op_sel_hi:[1,0,0]
	v_pk_mul_f32 v[184:185], v[128:129], v[0:1] op_sel_hi:[1,0]
	v_ashrrev_i32_e32 v145, 31, v144
	v_pk_fma_f32 v[188:189], v[128:129], v[138:139], v[184:185] op_sel:[0,0,1] op_sel_hi:[1,1,0] neg_lo:[0,0,1] neg_hi:[0,0,1]
	v_pk_fma_f32 v[128:129], v[128:129], v[138:139], v[184:185] op_sel:[0,0,1] op_sel_hi:[1,0,0]
	v_pk_mul_f32 v[184:185], v[122:123], v[132:133] op_sel:[0,1]
	v_cvt_pk_bf16_f32 v126, v186, v127
	v_pk_fma_f32 v[190:191], v[122:123], v[132:133], v[184:185] op_sel:[0,0,1] op_sel_hi:[1,1,0] neg_lo:[0,0,1] neg_hi:[0,0,1]
	v_pk_fma_f32 v[122:123], v[122:123], v[132:133], v[184:185] op_sel:[0,0,1] op_sel_hi:[1,0,0]
	v_mov_b32_e32 v184, v135
	v_pk_mul_f32 v[192:193], v[124:125], v[184:185] op_sel_hi:[1,0]
	v_cvt_pk_bf16_f32 v128, v190, v123
	v_pk_fma_f32 v[194:195], v[124:125], v[134:135], v[192:193] op_sel:[0,0,1] op_sel_hi:[1,1,0] neg_lo:[0,0,1] neg_hi:[0,0,1]
	v_pk_fma_f32 v[124:125], v[124:125], v[134:135], v[192:193] op_sel:[0,0,1] op_sel_hi:[1,0,0]
	v_mov_b64_e32 v[122:123], s[8:9]
	v_cvt_pk_bf16_f32 v127, v188, v129
	v_cvt_pk_bf16_f32 v129, v194, v125
	v_mad_i64_i32 v[186:187], s[0:1], v196, s47, v[122:123]
	v_lshlrev_b64 v[124:125], 1, v[144:145]
	v_lshl_add_u64 v[144:145], v[186:187], 0, v[124:125]
	global_store_dwordx4 v[144:145], v[126:129], off
	s_nop 1
	v_pk_mul_f32 v[126:127], v[118:119], v[136:137] op_sel:[0,1]
	s_nop 0
	v_pk_fma_f32 v[128:129], v[118:119], v[136:137], v[126:127] op_sel:[0,0,1] op_sel_hi:[1,1,0] neg_lo:[0,0,1] neg_hi:[0,0,1]
	v_pk_fma_f32 v[118:119], v[118:119], v[136:137], v[126:127] op_sel:[0,0,1] op_sel_hi:[1,0,0]
	v_pk_mul_f32 v[126:127], v[120:121], v[0:1] op_sel_hi:[1,0]
	s_nop 0
	v_pk_fma_f32 v[136:137], v[120:121], v[138:139], v[126:127] op_sel:[0,0,1] op_sel_hi:[1,1,0] neg_lo:[0,0,1] neg_hi:[0,0,1]
	v_pk_fma_f32 v[120:121], v[120:121], v[138:139], v[126:127] op_sel:[0,0,1] op_sel_hi:[1,0,0]
	v_pk_mul_f32 v[126:127], v[110:111], v[132:133] op_sel:[0,1]
	s_nop 0
	v_pk_fma_f32 v[138:139], v[110:111], v[132:133], v[126:127] op_sel:[0,0,1] op_sel_hi:[1,1,0] neg_lo:[0,0,1] neg_hi:[0,0,1]
	v_pk_fma_f32 v[126:127], v[110:111], v[132:133], v[126:127] op_sel:[0,0,1] op_sel_hi:[1,0,0]
	v_pk_mul_f32 v[110:111], v[112:113], v[184:185] op_sel_hi:[1,0]
	s_nop 0
	v_pk_fma_f32 v[132:133], v[112:113], v[134:135], v[110:111] op_sel:[0,0,1] op_sel_hi:[1,1,0] neg_lo:[0,0,1] neg_hi:[0,0,1]
	v_pk_fma_f32 v[112:113], v[112:113], v[134:135], v[110:111] op_sel:[0,0,1] op_sel_hi:[1,0,0]
	v_cvt_pk_bf16_f32 v110, v128, v119
	v_cvt_pk_bf16_f32 v111, v136, v121
	v_cvt_pk_bf16_f32 v112, v138, v127
	v_cvt_pk_bf16_f32 v113, v132, v113
	global_store_dwordx4 v[144:145], v[110:113], off offset:256
	s_nop 1
	v_pk_mul_f32 v[110:111], v[114:115], v[152:153] op_sel:[0,1]
	v_mov_b32_e32 v0, v155
	v_pk_fma_f32 v[112:113], v[114:115], v[152:153], v[110:111] op_sel:[0,0,1] op_sel_hi:[1,1,0] neg_lo:[0,0,1] neg_hi:[0,0,1]
	v_pk_fma_f32 v[110:111], v[114:115], v[152:153], v[110:111] op_sel:[0,0,1] op_sel_hi:[1,0,0]
	v_pk_mul_f32 v[114:115], v[116:117], v[0:1] op_sel_hi:[1,0]
	v_mov_b32_e32 v110, v143
	v_pk_fma_f32 v[118:119], v[116:117], v[154:155], v[114:115] op_sel:[0,0,1] op_sel_hi:[1,1,0] neg_lo:[0,0,1] neg_hi:[0,0,1]
	v_pk_fma_f32 v[114:115], v[116:117], v[154:155], v[114:115] op_sel:[0,0,1] op_sel_hi:[1,0,0]
	v_pk_mul_f32 v[116:117], v[106:107], v[140:141] op_sel:[0,1]
	s_nop 0
	v_pk_fma_f32 v[120:121], v[106:107], v[140:141], v[116:117] op_sel:[0,0,1] op_sel_hi:[1,1,0] neg_lo:[0,0,1] neg_hi:[0,0,1]
	v_pk_fma_f32 v[116:117], v[106:107], v[140:141], v[116:117] op_sel:[0,0,1] op_sel_hi:[1,0,0]
	v_pk_mul_f32 v[106:107], v[108:109], v[110:111] op_sel_hi:[1,0]
	s_nop 0
	v_pk_fma_f32 v[126:127], v[108:109], v[142:143], v[106:107] op_sel:[0,0,1] op_sel_hi:[1,1,0] neg_lo:[0,0,1] neg_hi:[0,0,1]
	v_pk_fma_f32 v[108:109], v[108:109], v[142:143], v[106:107] op_sel:[0,0,1] op_sel_hi:[1,0,0]
	v_cvt_pk_bf16_f32 v106, v112, v111
	v_mad_i64_i32 v[112:113], s[0:1], v175, s47, v[122:123]
	v_cvt_pk_bf16_f32 v107, v118, v115
	v_cvt_pk_bf16_f32 v108, v120, v117
	v_cvt_pk_bf16_f32 v109, v126, v109
	v_lshl_add_u64 v[112:113], v[112:113], 0, v[124:125]
	global_store_dwordx4 v[112:113], v[106:109], off
	s_nop 1
	v_pk_mul_f32 v[106:107], v[102:103], v[152:153] op_sel:[0,1]
	s_nop 0
	v_pk_fma_f32 v[108:109], v[102:103], v[152:153], v[106:107] op_sel:[0,0,1] op_sel_hi:[1,1,0] neg_lo:[0,0,1] neg_hi:[0,0,1]
	v_pk_fma_f32 v[102:103], v[102:103], v[152:153], v[106:107] op_sel:[0,0,1] op_sel_hi:[1,0,0]
	v_pk_mul_f32 v[106:107], v[104:105], v[0:1] op_sel_hi:[1,0]
	s_nop 0
	v_pk_fma_f32 v[114:115], v[104:105], v[154:155], v[106:107] op_sel:[0,0,1] op_sel_hi:[1,1,0] neg_lo:[0,0,1] neg_hi:[0,0,1]
	v_pk_fma_f32 v[104:105], v[104:105], v[154:155], v[106:107] op_sel:[0,0,1] op_sel_hi:[1,0,0]
	v_pk_mul_f32 v[106:107], v[94:95], v[140:141] op_sel:[0,1]
	s_nop 0
	v_pk_fma_f32 v[116:117], v[94:95], v[140:141], v[106:107] op_sel:[0,0,1] op_sel_hi:[1,1,0] neg_lo:[0,0,1] neg_hi:[0,0,1]
	v_pk_fma_f32 v[106:107], v[94:95], v[140:141], v[106:107] op_sel:[0,0,1] op_sel_hi:[1,0,0]
	v_pk_mul_f32 v[94:95], v[96:97], v[110:111] op_sel_hi:[1,0]
	s_nop 0
	v_pk_fma_f32 v[110:111], v[96:97], v[142:143], v[94:95] op_sel:[0,0,1] op_sel_hi:[1,1,0] neg_lo:[0,0,1] neg_hi:[0,0,1]
	v_pk_fma_f32 v[96:97], v[96:97], v[142:143], v[94:95] op_sel:[0,0,1] op_sel_hi:[1,0,0]
	v_cvt_pk_bf16_f32 v94, v108, v103
	v_cvt_pk_bf16_f32 v95, v114, v105
	v_cvt_pk_bf16_f32 v96, v116, v107
	v_cvt_pk_bf16_f32 v97, v110, v97
	global_store_dwordx4 v[112:113], v[94:97], off offset:256
	s_nop 1
	v_add_u32_e32 v147, 0x80, v196
	v_mul_hi_i32 v0, v147, s63
	v_lshrrev_b32_e32 v112, 31, v0
	v_ashrrev_i32_e32 v0, 10, v0
	v_add_u32_e32 v0, v0, v112
	v_mul_i32_i24_e32 v0, 0x880, v0
	v_add_u32_e32 v199, 0x90, v196
	v_sub_u32_e32 v112, v147, v0
	v_mul_hi_i32 v0, v199, s63
	v_lshrrev_b32_e32 v126, 31, v0
	v_ashrrev_i32_e32 v0, 10, v0
	v_add_u32_e32 v0, v0, v126
	v_mul_i32_i24_e32 v0, 0x880, v0
	v_add_u32_e32 v211, 0xa0, v196
	v_sub_u32_e32 v126, v199, v0
	v_mul_hi_i32 v0, v211, s63
	v_lshrrev_b32_e32 v136, 31, v0
	v_ashrrev_i32_e32 v0, 10, v0
	v_add_u32_e32 v0, v0, v136
	v_mul_i32_i24_e32 v0, 0x880, v0
	v_add_u32_e32 v215, 0xb0, v196
	v_sub_u32_e32 v136, v211, v0
	v_mul_hi_i32 v0, v215, s63
	v_lshrrev_b32_e32 v152, 31, v0
	v_ashrrev_i32_e32 v0, 10, v0
	v_add_u32_e32 v0, v0, v152
	v_mul_i32_i24_e32 v0, 0x880, v0
	v_sub_u32_e32 v152, v215, v0
	v_ashrrev_i32_e32 v113, 31, v112
	v_ashrrev_i32_e32 v127, 31, v126
	v_ashrrev_i32_e32 v137, 31, v136
	v_ashrrev_i32_e32 v153, 31, v152
	v_lshlrev_b64 v[112:113], 8, v[112:113]
	v_lshlrev_b64 v[126:127], 8, v[126:127]
	v_lshlrev_b64 v[136:137], 8, v[136:137]
	v_lshlrev_b64 v[152:153], 8, v[152:153]
	v_lshl_add_u64 v[116:117], v[130:131], 0, v[112:113]
	v_lshl_add_u64 v[132:133], v[130:131], 0, v[126:127]
	v_lshl_add_u64 v[140:141], v[130:131], 0, v[136:137]
	v_lshl_add_u64 v[184:185], v[130:131], 0, v[152:153]
	global_load_dwordx4 v[112:115], v[116:117], off offset:16
	s_nop 0
	global_load_dwordx4 v[116:119], v[116:117], off
	s_nop 0
	global_load_dwordx4 v[126:129], v[132:133], off offset:16
	s_nop 0
	global_load_dwordx4 v[132:135], v[132:133], off
	s_nop 0
	global_load_dwordx4 v[136:139], v[140:141], off offset:16
	s_nop 0
	global_load_dwordx4 v[140:143], v[140:141], off
	s_nop 0
	global_load_dwordx4 v[152:155], v[184:185], off offset:16
	s_nop 0
	global_load_dwordx4 v[184:187], v[184:185], off
	s_nop 1
	v_pk_mul_f32 v[94:95], v[98:99], v[170:171] op_sel:[0,1]
	v_mov_b32_e32 v0, v173
	v_pk_fma_f32 v[96:97], v[98:99], v[170:171], v[94:95] op_sel:[0,0,1] op_sel_hi:[1,1,0] neg_lo:[0,0,1] neg_hi:[0,0,1]
	v_pk_fma_f32 v[94:95], v[98:99], v[170:171], v[94:95] op_sel:[0,0,1] op_sel_hi:[1,0,0]
	v_pk_mul_f32 v[98:99], v[100:101], v[0:1] op_sel_hi:[1,0]
	v_mov_b32_e32 v94, v169
	v_pk_fma_f32 v[102:103], v[100:101], v[172:173], v[98:99] op_sel:[0,0,1] op_sel_hi:[1,1,0] neg_lo:[0,0,1] neg_hi:[0,0,1]
	v_pk_fma_f32 v[98:99], v[100:101], v[172:173], v[98:99] op_sel:[0,0,1] op_sel_hi:[1,0,0]
	v_pk_mul_f32 v[100:101], v[90:91], v[166:167] op_sel:[0,1]
	s_nop 0
	v_pk_fma_f32 v[104:105], v[90:91], v[166:167], v[100:101] op_sel:[0,0,1] op_sel_hi:[1,1,0] neg_lo:[0,0,1] neg_hi:[0,0,1]
	v_pk_fma_f32 v[100:101], v[90:91], v[166:167], v[100:101] op_sel:[0,0,1] op_sel_hi:[1,0,0]
	v_pk_mul_f32 v[90:91], v[92:93], v[94:95] op_sel_hi:[1,0]
	s_nop 0
	v_pk_fma_f32 v[106:107], v[92:93], v[168:169], v[90:91] op_sel:[0,0,1] op_sel_hi:[1,1,0] neg_lo:[0,0,1] neg_hi:[0,0,1]
	v_pk_fma_f32 v[92:93], v[92:93], v[168:169], v[90:91] op_sel:[0,0,1] op_sel_hi:[1,0,0]
	v_cvt_pk_bf16_f32 v90, v96, v95
	v_mad_i64_i32 v[96:97], s[0:1], v197, s47, v[122:123]
	v_cvt_pk_bf16_f32 v91, v102, v99
	v_cvt_pk_bf16_f32 v92, v104, v101
	v_cvt_pk_bf16_f32 v93, v106, v93
	v_lshl_add_u64 v[96:97], v[96:97], 0, v[124:125]
	global_store_dwordx4 v[96:97], v[90:93], off
	s_nop 1
	v_pk_mul_f32 v[90:91], v[86:87], v[170:171] op_sel:[0,1]
	s_nop 0
	v_pk_fma_f32 v[92:93], v[86:87], v[170:171], v[90:91] op_sel:[0,0,1] op_sel_hi:[1,1,0] neg_lo:[0,0,1] neg_hi:[0,0,1]
	v_pk_fma_f32 v[86:87], v[86:87], v[170:171], v[90:91] op_sel:[0,0,1] op_sel_hi:[1,0,0]
	v_pk_mul_f32 v[90:91], v[88:89], v[0:1] op_sel_hi:[1,0]
	s_nop 0
	v_pk_fma_f32 v[98:99], v[88:89], v[172:173], v[90:91] op_sel:[0,0,1] op_sel_hi:[1,1,0] neg_lo:[0,0,1] neg_hi:[0,0,1]
	v_pk_fma_f32 v[88:89], v[88:89], v[172:173], v[90:91] op_sel:[0,0,1] op_sel_hi:[1,0,0]
	v_pk_mul_f32 v[90:91], v[78:79], v[166:167] op_sel:[0,1]
	s_nop 0
	v_pk_fma_f32 v[100:101], v[78:79], v[166:167], v[90:91] op_sel:[0,0,1] op_sel_hi:[1,1,0] neg_lo:[0,0,1] neg_hi:[0,0,1]
	v_pk_fma_f32 v[90:91], v[78:79], v[166:167], v[90:91] op_sel:[0,0,1] op_sel_hi:[1,0,0]
	v_pk_mul_f32 v[78:79], v[80:81], v[94:95] op_sel_hi:[1,0]
	s_nop 0
	v_pk_fma_f32 v[94:95], v[80:81], v[168:169], v[78:79] op_sel:[0,0,1] op_sel_hi:[1,1,0] neg_lo:[0,0,1] neg_hi:[0,0,1]
	v_pk_fma_f32 v[80:81], v[80:81], v[168:169], v[78:79] op_sel:[0,0,1] op_sel_hi:[1,0,0]
	v_cvt_pk_bf16_f32 v78, v92, v87
	v_cvt_pk_bf16_f32 v79, v98, v89
	v_cvt_pk_bf16_f32 v80, v100, v91
	v_cvt_pk_bf16_f32 v81, v94, v81
	global_store_dwordx4 v[96:97], v[78:81], off offset:256
	s_nop 1
	v_pk_mul_f32 v[78:79], v[82:83], v[180:181] op_sel:[0,1]
	v_mov_b32_e32 v0, v183
	v_pk_fma_f32 v[80:81], v[82:83], v[180:181], v[78:79] op_sel:[0,0,1] op_sel_hi:[1,1,0] neg_lo:[0,0,1] neg_hi:[0,0,1]
	v_pk_fma_f32 v[78:79], v[82:83], v[180:181], v[78:79] op_sel:[0,0,1] op_sel_hi:[1,0,0]
	v_pk_mul_f32 v[82:83], v[84:85], v[0:1] op_sel_hi:[1,0]
	v_mov_b32_e32 v78, v179
	v_pk_fma_f32 v[86:87], v[84:85], v[182:183], v[82:83] op_sel:[0,0,1] op_sel_hi:[1,1,0] neg_lo:[0,0,1] neg_hi:[0,0,1]
	v_pk_fma_f32 v[82:83], v[84:85], v[182:183], v[82:83] op_sel:[0,0,1] op_sel_hi:[1,0,0]
	v_pk_mul_f32 v[84:85], v[74:75], v[176:177] op_sel:[0,1]
	s_nop 0
	v_pk_fma_f32 v[88:89], v[74:75], v[176:177], v[84:85] op_sel:[0,0,1] op_sel_hi:[1,1,0] neg_lo:[0,0,1] neg_hi:[0,0,1]
	v_pk_fma_f32 v[84:85], v[74:75], v[176:177], v[84:85] op_sel:[0,0,1] op_sel_hi:[1,0,0]
	v_pk_mul_f32 v[74:75], v[76:77], v[78:79] op_sel_hi:[1,0]
	s_nop 0
	v_pk_fma_f32 v[90:91], v[76:77], v[178:179], v[74:75] op_sel:[0,0,1] op_sel_hi:[1,1,0] neg_lo:[0,0,1] neg_hi:[0,0,1]
	v_pk_fma_f32 v[76:77], v[76:77], v[178:179], v[74:75] op_sel:[0,0,1] op_sel_hi:[1,0,0]
	v_cvt_pk_bf16_f32 v74, v80, v79
	v_mad_i64_i32 v[80:81], s[0:1], v198, s47, v[122:123]
	v_cvt_pk_bf16_f32 v75, v86, v83
	v_cvt_pk_bf16_f32 v76, v88, v85
	v_cvt_pk_bf16_f32 v77, v90, v77
	v_lshl_add_u64 v[80:81], v[80:81], 0, v[124:125]
	global_store_dwordx4 v[80:81], v[74:77], off
	s_nop 1
	v_pk_mul_f32 v[74:75], v[70:71], v[180:181] op_sel:[0,1]
	s_nop 0
	v_pk_fma_f32 v[76:77], v[70:71], v[180:181], v[74:75] op_sel:[0,0,1] op_sel_hi:[1,1,0] neg_lo:[0,0,1] neg_hi:[0,0,1]
	v_pk_fma_f32 v[70:71], v[70:71], v[180:181], v[74:75] op_sel:[0,0,1] op_sel_hi:[1,0,0]
	v_pk_mul_f32 v[74:75], v[72:73], v[0:1] op_sel_hi:[1,0]
	s_nop 0
	v_pk_fma_f32 v[82:83], v[72:73], v[182:183], v[74:75] op_sel:[0,0,1] op_sel_hi:[1,1,0] neg_lo:[0,0,1] neg_hi:[0,0,1]
	v_pk_fma_f32 v[72:73], v[72:73], v[182:183], v[74:75] op_sel:[0,0,1] op_sel_hi:[1,0,0]
	v_pk_mul_f32 v[74:75], v[66:67], v[176:177] op_sel:[0,1]
	s_nop 0
	v_pk_fma_f32 v[84:85], v[66:67], v[176:177], v[74:75] op_sel:[0,0,1] op_sel_hi:[1,1,0] neg_lo:[0,0,1] neg_hi:[0,0,1]
	v_pk_fma_f32 v[74:75], v[66:67], v[176:177], v[74:75] op_sel:[0,0,1] op_sel_hi:[1,0,0]
	v_pk_mul_f32 v[66:67], v[68:69], v[78:79] op_sel_hi:[1,0]
	s_nop 0
	v_pk_fma_f32 v[78:79], v[68:69], v[178:179], v[66:67] op_sel:[0,0,1] op_sel_hi:[1,1,0] neg_lo:[0,0,1] neg_hi:[0,0,1]
	v_pk_fma_f32 v[68:69], v[68:69], v[178:179], v[66:67] op_sel:[0,0,1] op_sel_hi:[1,0,0]
	v_cvt_pk_bf16_f32 v66, v76, v71
	v_cvt_pk_bf16_f32 v67, v82, v73
	v_cvt_pk_bf16_f32 v68, v84, v75
	v_cvt_pk_bf16_f32 v69, v78, v69
	global_store_dwordx4 v[80:81], v[66:69], off offset:256
	s_waitcnt vmcnt(4)
	v_pk_mul_f32 v[98:99], v[62:63], v[116:117] op_sel:[0,1]
	v_mov_b32_e32 v0, v119
	v_pk_fma_f32 v[100:101], v[62:63], v[116:117], v[98:99] op_sel:[0,0,1] op_sel_hi:[1,1,0] neg_lo:[0,0,1] neg_hi:[0,0,1]
	v_pk_fma_f32 v[62:63], v[62:63], v[116:117], v[98:99] op_sel:[0,0,1] op_sel_hi:[1,0,0]
	v_pk_mul_f32 v[98:99], v[64:65], v[0:1] op_sel_hi:[1,0]
	v_mov_b32_e32 v62, v115
	v_pk_fma_f32 v[102:103], v[64:65], v[118:119], v[98:99] op_sel:[0,0,1] op_sel_hi:[1,1,0] neg_lo:[0,0,1] neg_hi:[0,0,1]
	v_pk_fma_f32 v[64:65], v[64:65], v[118:119], v[98:99] op_sel:[0,0,1] op_sel_hi:[1,0,0]
	v_pk_mul_f32 v[98:99], v[58:59], v[112:113] op_sel:[0,1]
	s_nop 0
	v_pk_fma_f32 v[104:105], v[58:59], v[112:113], v[98:99] op_sel:[0,0,1] op_sel_hi:[1,1,0] neg_lo:[0,0,1] neg_hi:[0,0,1]
	v_pk_fma_f32 v[98:99], v[58:59], v[112:113], v[98:99] op_sel:[0,0,1] op_sel_hi:[1,0,0]
	v_pk_mul_f32 v[58:59], v[60:61], v[62:63] op_sel_hi:[1,0]
	s_nop 0
	v_pk_fma_f32 v[106:107], v[60:61], v[114:115], v[58:59] op_sel:[0,0,1] op_sel_hi:[1,1,0] neg_lo:[0,0,1] neg_hi:[0,0,1]
	v_pk_fma_f32 v[60:61], v[60:61], v[114:115], v[58:59] op_sel:[0,0,1] op_sel_hi:[1,0,0]
	v_cvt_pk_bf16_f32 v59, v102, v65
	v_mad_i64_i32 v[64:65], s[0:1], v147, s47, v[122:123]
	v_cvt_pk_bf16_f32 v58, v100, v63
	v_cvt_pk_bf16_f32 v60, v104, v99
	v_cvt_pk_bf16_f32 v61, v106, v61
	v_lshl_add_u64 v[64:65], v[64:65], 0, v[124:125]
	global_store_dwordx4 v[64:65], v[58:61], off
	s_nop 1
	v_pk_mul_f32 v[58:59], v[54:55], v[116:117] op_sel:[0,1]
	s_nop 0
	v_pk_fma_f32 v[60:61], v[54:55], v[116:117], v[58:59] op_sel:[0,0,1] op_sel_hi:[1,1,0] neg_lo:[0,0,1] neg_hi:[0,0,1]
	v_pk_fma_f32 v[54:55], v[54:55], v[116:117], v[58:59] op_sel:[0,0,1] op_sel_hi:[1,0,0]
	v_pk_mul_f32 v[58:59], v[56:57], v[0:1] op_sel_hi:[1,0]
	s_nop 0
	v_pk_fma_f32 v[70:71], v[56:57], v[118:119], v[58:59] op_sel:[0,0,1] op_sel_hi:[1,1,0] neg_lo:[0,0,1] neg_hi:[0,0,1]
	v_pk_fma_f32 v[56:57], v[56:57], v[118:119], v[58:59] op_sel:[0,0,1] op_sel_hi:[1,0,0]
	v_pk_mul_f32 v[58:59], v[46:47], v[112:113] op_sel:[0,1]
	s_nop 0
	v_pk_fma_f32 v[72:73], v[46:47], v[112:113], v[58:59] op_sel:[0,0,1] op_sel_hi:[1,1,0] neg_lo:[0,0,1] neg_hi:[0,0,1]
	v_pk_fma_f32 v[58:59], v[46:47], v[112:113], v[58:59] op_sel:[0,0,1] op_sel_hi:[1,0,0]
	v_pk_mul_f32 v[46:47], v[48:49], v[62:63] op_sel_hi:[1,0]
	s_nop 0
	v_pk_fma_f32 v[62:63], v[48:49], v[114:115], v[46:47] op_sel:[0,0,1] op_sel_hi:[1,1,0] neg_lo:[0,0,1] neg_hi:[0,0,1]
	v_pk_fma_f32 v[48:49], v[48:49], v[114:115], v[46:47] op_sel:[0,0,1] op_sel_hi:[1,0,0]
	v_cvt_pk_bf16_f32 v46, v60, v55
	v_cvt_pk_bf16_f32 v47, v70, v57
	v_cvt_pk_bf16_f32 v48, v72, v59
	v_cvt_pk_bf16_f32 v49, v62, v49
	global_store_dwordx4 v[64:65], v[46:49], off offset:256
	s_nop 1
	v_pk_mul_f32 v[46:47], v[50:51], v[132:133] op_sel:[0,1]
	v_mov_b32_e32 v0, v135
	v_pk_fma_f32 v[48:49], v[50:51], v[132:133], v[46:47] op_sel:[0,0,1] op_sel_hi:[1,1,0] neg_lo:[0,0,1] neg_hi:[0,0,1]
	v_pk_fma_f32 v[46:47], v[50:51], v[132:133], v[46:47] op_sel:[0,0,1] op_sel_hi:[1,0,0]
	v_pk_mul_f32 v[50:51], v[52:53], v[0:1] op_sel_hi:[1,0]
	v_mov_b32_e32 v46, v129
	v_pk_fma_f32 v[54:55], v[52:53], v[134:135], v[50:51] op_sel:[0,0,1] op_sel_hi:[1,1,0] neg_lo:[0,0,1] neg_hi:[0,0,1]
	v_pk_fma_f32 v[50:51], v[52:53], v[134:135], v[50:51] op_sel:[0,0,1] op_sel_hi:[1,0,0]
	v_pk_mul_f32 v[52:53], v[42:43], v[126:127] op_sel:[0,1]
	s_nop 0
	v_pk_fma_f32 v[56:57], v[42:43], v[126:127], v[52:53] op_sel:[0,0,1] op_sel_hi:[1,1,0] neg_lo:[0,0,1] neg_hi:[0,0,1]
	v_pk_fma_f32 v[52:53], v[42:43], v[126:127], v[52:53] op_sel:[0,0,1] op_sel_hi:[1,0,0]
	v_pk_mul_f32 v[42:43], v[44:45], v[46:47] op_sel_hi:[1,0]
	s_nop 0
	v_pk_fma_f32 v[58:59], v[44:45], v[128:129], v[42:43] op_sel:[0,0,1] op_sel_hi:[1,1,0] neg_lo:[0,0,1] neg_hi:[0,0,1]
	v_pk_fma_f32 v[44:45], v[44:45], v[128:129], v[42:43] op_sel:[0,0,1] op_sel_hi:[1,0,0]
	v_cvt_pk_bf16_f32 v42, v48, v47
	v_mad_i64_i32 v[48:49], s[0:1], v199, s47, v[122:123]
	v_cvt_pk_bf16_f32 v43, v54, v51
	v_cvt_pk_bf16_f32 v44, v56, v53
	v_cvt_pk_bf16_f32 v45, v58, v45
	v_lshl_add_u64 v[48:49], v[48:49], 0, v[124:125]
	global_store_dwordx4 v[48:49], v[42:45], off
	s_nop 1
	v_pk_mul_f32 v[42:43], v[38:39], v[132:133] op_sel:[0,1]
	s_nop 0
	v_pk_fma_f32 v[44:45], v[38:39], v[132:133], v[42:43] op_sel:[0,0,1] op_sel_hi:[1,1,0] neg_lo:[0,0,1] neg_hi:[0,0,1]
	v_pk_fma_f32 v[38:39], v[38:39], v[132:133], v[42:43] op_sel:[0,0,1] op_sel_hi:[1,0,0]
	v_pk_mul_f32 v[42:43], v[40:41], v[0:1] op_sel_hi:[1,0]
	s_nop 0
	v_pk_fma_f32 v[50:51], v[40:41], v[134:135], v[42:43] op_sel:[0,0,1] op_sel_hi:[1,1,0] neg_lo:[0,0,1] neg_hi:[0,0,1]
	v_pk_fma_f32 v[40:41], v[40:41], v[134:135], v[42:43] op_sel:[0,0,1] op_sel_hi:[1,0,0]
	v_pk_mul_f32 v[42:43], v[30:31], v[126:127] op_sel:[0,1]
	s_nop 0
	v_pk_fma_f32 v[52:53], v[30:31], v[126:127], v[42:43] op_sel:[0,0,1] op_sel_hi:[1,1,0] neg_lo:[0,0,1] neg_hi:[0,0,1]
	v_pk_fma_f32 v[42:43], v[30:31], v[126:127], v[42:43] op_sel:[0,0,1] op_sel_hi:[1,0,0]
	v_pk_mul_f32 v[30:31], v[32:33], v[46:47] op_sel_hi:[1,0]
	s_nop 0
	v_pk_fma_f32 v[46:47], v[32:33], v[128:129], v[30:31] op_sel:[0,0,1] op_sel_hi:[1,1,0] neg_lo:[0,0,1] neg_hi:[0,0,1]
	v_pk_fma_f32 v[32:33], v[32:33], v[128:129], v[30:31] op_sel:[0,0,1] op_sel_hi:[1,0,0]
	v_cvt_pk_bf16_f32 v30, v44, v39
	v_cvt_pk_bf16_f32 v31, v50, v41
	v_cvt_pk_bf16_f32 v32, v52, v43
	v_cvt_pk_bf16_f32 v33, v46, v33
	global_store_dwordx4 v[48:49], v[30:33], off offset:256
	s_nop 1
	v_pk_mul_f32 v[30:31], v[34:35], v[140:141] op_sel:[0,1]
	v_mov_b32_e32 v0, v143
	v_pk_fma_f32 v[32:33], v[34:35], v[140:141], v[30:31] op_sel:[0,0,1] op_sel_hi:[1,1,0] neg_lo:[0,0,1] neg_hi:[0,0,1]
	v_pk_fma_f32 v[30:31], v[34:35], v[140:141], v[30:31] op_sel:[0,0,1] op_sel_hi:[1,0,0]
	v_pk_mul_f32 v[34:35], v[36:37], v[0:1] op_sel_hi:[1,0]
	v_mov_b32_e32 v30, v139
	v_pk_fma_f32 v[38:39], v[36:37], v[142:143], v[34:35] op_sel:[0,0,1] op_sel_hi:[1,1,0] neg_lo:[0,0,1] neg_hi:[0,0,1]
	v_pk_fma_f32 v[34:35], v[36:37], v[142:143], v[34:35] op_sel:[0,0,1] op_sel_hi:[1,0,0]
	v_pk_mul_f32 v[36:37], v[26:27], v[136:137] op_sel:[0,1]
	s_nop 0
	v_pk_fma_f32 v[40:41], v[26:27], v[136:137], v[36:37] op_sel:[0,0,1] op_sel_hi:[1,1,0] neg_lo:[0,0,1] neg_hi:[0,0,1]
	v_pk_fma_f32 v[36:37], v[26:27], v[136:137], v[36:37] op_sel:[0,0,1] op_sel_hi:[1,0,0]
	v_pk_mul_f32 v[26:27], v[28:29], v[30:31] op_sel_hi:[1,0]
	s_nop 0
	v_pk_fma_f32 v[42:43], v[28:29], v[138:139], v[26:27] op_sel:[0,0,1] op_sel_hi:[1,1,0] neg_lo:[0,0,1] neg_hi:[0,0,1]
	v_pk_fma_f32 v[28:29], v[28:29], v[138:139], v[26:27] op_sel:[0,0,1] op_sel_hi:[1,0,0]
	v_cvt_pk_bf16_f32 v26, v32, v31
	v_mad_i64_i32 v[32:33], s[0:1], v211, s47, v[122:123]
	v_cvt_pk_bf16_f32 v27, v38, v35
	v_cvt_pk_bf16_f32 v28, v40, v37
	v_cvt_pk_bf16_f32 v29, v42, v29
	v_lshl_add_u64 v[32:33], v[32:33], 0, v[124:125]
	global_store_dwordx4 v[32:33], v[26:29], off
	s_nop 1
	v_pk_mul_f32 v[26:27], v[22:23], v[140:141] op_sel:[0,1]
	s_nop 0
	v_pk_fma_f32 v[28:29], v[22:23], v[140:141], v[26:27] op_sel:[0,0,1] op_sel_hi:[1,1,0] neg_lo:[0,0,1] neg_hi:[0,0,1]
	v_pk_fma_f32 v[22:23], v[22:23], v[140:141], v[26:27] op_sel:[0,0,1] op_sel_hi:[1,0,0]
	v_pk_mul_f32 v[26:27], v[24:25], v[0:1] op_sel_hi:[1,0]
	s_nop 0
	v_pk_fma_f32 v[34:35], v[24:25], v[142:143], v[26:27] op_sel:[0,0,1] op_sel_hi:[1,1,0] neg_lo:[0,0,1] neg_hi:[0,0,1]
	v_pk_fma_f32 v[24:25], v[24:25], v[142:143], v[26:27] op_sel:[0,0,1] op_sel_hi:[1,0,0]
	v_pk_mul_f32 v[26:27], v[14:15], v[136:137] op_sel:[0,1]
	s_nop 0
	v_pk_fma_f32 v[36:37], v[14:15], v[136:137], v[26:27] op_sel:[0,0,1] op_sel_hi:[1,1,0] neg_lo:[0,0,1] neg_hi:[0,0,1]
	v_pk_fma_f32 v[26:27], v[14:15], v[136:137], v[26:27] op_sel:[0,0,1] op_sel_hi:[1,0,0]
	v_pk_mul_f32 v[14:15], v[16:17], v[30:31] op_sel_hi:[1,0]
	s_nop 0
	v_pk_fma_f32 v[30:31], v[16:17], v[138:139], v[14:15] op_sel:[0,0,1] op_sel_hi:[1,1,0] neg_lo:[0,0,1] neg_hi:[0,0,1]
	v_pk_fma_f32 v[16:17], v[16:17], v[138:139], v[14:15] op_sel:[0,0,1] op_sel_hi:[1,0,0]
	v_cvt_pk_bf16_f32 v14, v28, v23
	v_cvt_pk_bf16_f32 v15, v34, v25
	v_cvt_pk_bf16_f32 v16, v36, v27
	v_cvt_pk_bf16_f32 v17, v30, v17
	global_store_dwordx4 v[32:33], v[14:17], off offset:256
	s_nop 1
	v_pk_mul_f32 v[14:15], v[18:19], v[184:185] op_sel:[0,1]
	v_mov_b32_e32 v0, v187
	v_pk_fma_f32 v[16:17], v[18:19], v[184:185], v[14:15] op_sel:[0,0,1] op_sel_hi:[1,1,0] neg_lo:[0,0,1] neg_hi:[0,0,1]
	v_pk_fma_f32 v[14:15], v[18:19], v[184:185], v[14:15] op_sel:[0,0,1] op_sel_hi:[1,0,0]
	v_pk_mul_f32 v[18:19], v[20:21], v[0:1] op_sel_hi:[1,0]
	v_mov_b32_e32 v14, v155
	v_pk_fma_f32 v[22:23], v[20:21], v[186:187], v[18:19] op_sel:[0,0,1] op_sel_hi:[1,1,0] neg_lo:[0,0,1] neg_hi:[0,0,1]
	v_pk_fma_f32 v[18:19], v[20:21], v[186:187], v[18:19] op_sel:[0,0,1] op_sel_hi:[1,0,0]
	v_pk_mul_f32 v[20:21], v[10:11], v[152:153] op_sel:[0,1]
	s_nop 0
	v_pk_fma_f32 v[24:25], v[10:11], v[152:153], v[20:21] op_sel:[0,0,1] op_sel_hi:[1,1,0] neg_lo:[0,0,1] neg_hi:[0,0,1]
	v_pk_fma_f32 v[20:21], v[10:11], v[152:153], v[20:21] op_sel:[0,0,1] op_sel_hi:[1,0,0]
	v_pk_mul_f32 v[10:11], v[12:13], v[14:15] op_sel_hi:[1,0]
	s_nop 0
	v_pk_fma_f32 v[26:27], v[12:13], v[154:155], v[10:11] op_sel:[0,0,1] op_sel_hi:[1,1,0] neg_lo:[0,0,1] neg_hi:[0,0,1]
	v_pk_fma_f32 v[12:13], v[12:13], v[154:155], v[10:11] op_sel:[0,0,1] op_sel_hi:[1,0,0]
	v_cvt_pk_bf16_f32 v10, v16, v15
	v_mad_i64_i32 v[16:17], s[0:1], v215, s47, v[122:123]
	v_cvt_pk_bf16_f32 v11, v22, v19
	v_cvt_pk_bf16_f32 v12, v24, v21
	v_cvt_pk_bf16_f32 v13, v26, v13
	v_lshl_add_u64 v[16:17], v[16:17], 0, v[124:125]
	global_store_dwordx4 v[16:17], v[10:13], off
	s_nop 1
	v_pk_mul_f32 v[10:11], v[6:7], v[184:185] op_sel:[0,1]
	s_nop 0
	v_pk_fma_f32 v[12:13], v[6:7], v[184:185], v[10:11] op_sel:[0,0,1] op_sel_hi:[1,1,0] neg_lo:[0,0,1] neg_hi:[0,0,1]
	v_pk_fma_f32 v[6:7], v[6:7], v[184:185], v[10:11] op_sel:[0,0,1] op_sel_hi:[1,0,0]
	v_pk_mul_f32 v[10:11], v[8:9], v[0:1] op_sel_hi:[1,0]
	s_nop 0
	v_pk_fma_f32 v[18:19], v[8:9], v[186:187], v[10:11] op_sel:[0,0,1] op_sel_hi:[1,1,0] neg_lo:[0,0,1] neg_hi:[0,0,1]
	v_pk_fma_f32 v[8:9], v[8:9], v[186:187], v[10:11] op_sel:[0,0,1] op_sel_hi:[1,0,0]
	v_pk_mul_f32 v[10:11], v[2:3], v[152:153] op_sel:[0,1]
	s_nop 0
	v_pk_fma_f32 v[20:21], v[2:3], v[152:153], v[10:11] op_sel:[0,0,1] op_sel_hi:[1,1,0] neg_lo:[0,0,1] neg_hi:[0,0,1]
	v_pk_fma_f32 v[10:11], v[2:3], v[152:153], v[10:11] op_sel:[0,0,1] op_sel_hi:[1,0,0]
	v_pk_mul_f32 v[2:3], v[4:5], v[14:15] op_sel_hi:[1,0]
	s_nop 0
	v_pk_fma_f32 v[14:15], v[4:5], v[154:155], v[2:3] op_sel:[0,0,1] op_sel_hi:[1,1,0] neg_lo:[0,0,1] neg_hi:[0,0,1]
	v_pk_fma_f32 v[4:5], v[4:5], v[154:155], v[2:3] op_sel:[0,0,1] op_sel_hi:[1,0,0]
	v_cvt_pk_bf16_f32 v2, v12, v7
	v_cvt_pk_bf16_f32 v3, v18, v9
	v_cvt_pk_bf16_f32 v4, v20, v11
	v_cvt_pk_bf16_f32 v5, v14, v5
	global_store_dwordx4 v[16:17], v[2:5], off offset:256
	s_branch .LBB0_128
